# store-traffic reduction phase 2: FFN-down of layers 1,2 no longer stores bf16 x (only A'=x*gm_next); mixer of layers 2,3 reconstructs x from A' * (1/gm) in f32
# speedup vs baseline: 1.0174x; 1.0091x over previous
.LBB0_1032:
	v_readlane_b32 s12, v250, 6
	s_cmp_eq_u32 s68, 0
	v_readlane_b32 s13, v250, 7
	v_readlane_b32 s14, v250, 8
	v_readlane_b32 s15, v250, 9
	s_cselect_b32 s11, s13, 0
	s_cselect_b32 s10, s12, 0
	s_mov_b32 s12, 0x13700000
	s_cmp_lt_u32 s68, 2
	s_cselect_b32 s12, 0x30900000, s12
	s_add_u32 s12, s6, s12
	s_addc_u32 s13, s7, 0
	s_lshl_b64 s[14:15], s[94:95], 2
	v_readlane_b32 s17, v250, 11
	s_add_u32 s1, s6, s14
	s_addc_u32 s17, s7, s15
	s_add_u32 s14, s1, 0x448000
	v_readlane_b32 s16, v250, 10
	s_addc_u32 s15, s17, 0
	s_add_u32 s16, s1, 0x420000
	v_readlane_b32 s18, v250, 12
	s_addc_u32 s17, s17, 0
	v_readlane_b32 s19, v250, 13
	v_readlane_b32 s20, v250, 14
	v_readlane_b32 s21, v250, 15
	s_add_u32 s18, s6, 0x13700000
	s_addc_u32 s19, s7, 0
	s_lshl_b64 s[20:21], s[38:39], 3
	s_add_u32 s1, s6, s20
	s_addc_u32 s6, s7, s21
	v_and_b32_e32 v3, 15, v2
	s_add_u32 s20, s1, 0x10000
	v_or_b32_e32 v4, s72, v3
	s_addc_u32 s21, s6, 0
	s_lshr_b32 s55, s0, 6
	v_and_b32_e32 v5, 48, v2
	v_lshlrev_b32_e32 v6, 6, v4
	s_movk_i32 s0, 0x3c0
	v_lshlrev_b32_e32 v4, 2, v4
	v_and_or_b32 v6, v6, s0, v5
	v_and_b32_e32 v4, 32, v4
	v_readlane_b32 s0, v254, 51
	v_lshlrev_b32_e32 v2, 2, v2
	v_lshl_or_b32 v3, v3, 6, v5
	v_bitop3_b32 v4, v6, s0, v4 bitop3:0xde
	v_and_b32_e32 v2, 32, v2
	v_readlane_b32 s0, v255, 0
	s_add_i32 s56, s45, 0x18000
	s_waitcnt vmcnt(2)
	s_barrier
	v_bitop3_b32 v2, v3, s0, v2 bitop3:0xde
	s_add_u32 s0, s30, 0x80
	s_addc_u32 s1, s31, 0
	s_mov_b32 m0, s56
	s_nop 0
	global_load_lds_dwordx4 v240, s[0:1]
	s_add_i32 s57, s45, 0x1a000
	s_add_i32 s58, s45, 0x8000
	s_mov_b32 m0, s57
	s_nop 0
	global_load_lds_dwordx4 v242, s[0:1]
	s_add_u32 s0, s34, 0x80
	s_addc_u32 s1, s35, 0
	s_mov_b32 m0, s58
	s_nop 0
	global_load_lds_dwordx4 v0, s[0:1]
	s_add_i32 s59, s45, 0xa000
	s_add_i32 s60, s45, 0x1c000
	s_mov_b32 m0, s59
	s_nop 0
	global_load_lds_dwordx4 v241, s[0:1]
	s_add_u32 s0, s8, 0x80
	s_addc_u32 s1, s9, 0
	s_mov_b32 m0, s60
	s_nop 0
	global_load_lds_dwordx4 v240, s[0:1]
	s_add_i32 s61, s45, 0x1e000
	s_mov_b32 m0, s61
	s_nop 0
	global_load_lds_dwordx4 v242, s[0:1]
	s_waitcnt vmcnt(6)
	s_add_i32 s62, s45, 0xc000
	s_add_i32 s63, s45, 0xe000
	v_readlane_b32 s22, v250, 16
	v_readlane_b32 s23, v250, 17
	s_cmp_lg_u64 s[10:11], 0
	v_readlane_b32 s6, v255, 32
	s_mov_b32 s36, 0
	v_readlane_b32 s24, v250, 18
	s_cselect_b64 s[22:23], -1, 0
	v_add_u32_e32 v243, 0, v2
	v_add_u32_e32 v244, 0, v4
	v_readlane_b32 s1, v255, 11
	s_mov_b32 s0, s6
	v_readlane_b32 s25, v250, 19
	v_readlane_b32 s26, v250, 20
	v_readlane_b32 s27, v250, 21
	s_barrier
	v_readlane_b32 s7, v255, 33
	s_branch .LBB0_1035

.LBB0_1055:
	v_mbcnt_lo_u32_b32 v146, -1, 0
	v_mbcnt_hi_u32_b32 v146, -1, v146
	s_lshl_b32 s1, s1, 8
	v_bfe_u32 v245, v146, 4, 2
	v_lshl_or_b32 v98, v245, 3, s1
	s_lshl_b32 s1, s0, 7
	v_or_b32_e32 v196, s82, v98
	s_and_b32 s1, s1, 0xfffff800
	v_add_u32_e32 v98, s1, v196
	v_ashrrev_i32_e32 v99, 31, v98
	v_lshlrev_b64 v[98:99], 2, v[98:99]
	v_lshl_add_u64 v[208:209], s[14:15], 0, v[98:99]
	s_mov_b32 s96, 0xfffb8000
	s_mov_b32 s97, -1
	v_lshl_add_u64 v[186:187], v[208:209], 0, s[96:97]
	v_lshl_add_u64 v[210:211], s[16:17], 0, v[98:99]
	flat_load_dwordx4 v[110:113], v[208:209]
	flat_load_dwordx4 v[106:109], v[208:209] offset:16
	flat_load_dwordx4 v[102:105], v[210:211]
	flat_load_dwordx4 v[98:101], v[210:211] offset:16
	s_lshl_b32 s0, s0, 8
	s_add_i32 s0, s0, s72
	v_and_or_b32 v178, v146, 15, s0
	v_ashrrev_i32_e32 v197, 31, v196
	v_ashrrev_i32_e32 v179, 31, v178
	v_cndmask_b32_e64 v146, 0, 1, s[22:23]
	v_cmp_ne_u32_e64 s[8:9], 1, v146
	s_andn2_b64 vcc, exec, s[22:23]
	v_lshlrev_b64 v[212:213], 13, v[178:179]
	v_lshl_add_u64 v[188:189], v[196:197], 2, s[10:11]
	v_or_b32_e32 v200, 16, v178
	v_or_b32_e32 v198, 32, v178
	v_or_b32_e32 v194, 48, v178
	s_cbranch_vccnz .LBB0_1065
	v_lshl_add_u64 v[146:147], v[188:189], 0, v[212:213]
	v_ashrrev_i32_e32 v201, 31, v200
	global_load_dwordx4 v[174:177], v[146:147], off offset:16
	global_load_dwordx4 v[170:173], v[146:147], off
	v_lshlrev_b64 v[146:147], 13, v[200:201]
	v_lshl_add_u64 v[146:147], v[188:189], 0, v[146:147]
	v_ashrrev_i32_e32 v199, 31, v198
	global_load_dwordx4 v[166:169], v[146:147], off offset:16
	global_load_dwordx4 v[162:165], v[146:147], off
	v_lshlrev_b64 v[146:147], 13, v[198:199]
	v_lshl_add_u64 v[146:147], v[188:189], 0, v[146:147]
	v_ashrrev_i32_e32 v195, 31, v194
	global_load_dwordx4 v[158:161], v[146:147], off offset:16
	global_load_dwordx4 v[154:157], v[146:147], off
	v_lshlrev_b64 v[146:147], 13, v[194:195]
	v_lshl_add_u64 v[146:147], v[188:189], 0, v[146:147]
	global_load_dwordx4 v[150:153], v[146:147], off offset:16
	s_nop 0
	global_load_dwordx4 v[146:149], v[146:147], off
	v_lshlrev_b64 v[214:215], 12, v[178:179]
	v_lshl_add_u64 v[226:227], v[196:197], 1, s[12:13]
	s_cbranch_execnz .LBB0_1058
.LBB0_1057:
	v_ashrrev_i32_e32 v199, 31, v198
	s_waitcnt vmcnt(0)
	global_load_dwordx4 v[218:221], v[186:187], off
	global_load_dwordx4 v[222:225], v[186:187], off offset:16
	v_lshlrev_b64 v[154:155], 12, v[198:199]
	v_ashrrev_i32_e32 v201, 31, v200
	v_lshl_add_u64 v[154:155], v[226:227], 0, v[154:155]
	v_ashrrev_i32_e32 v195, 31, v194
	v_lshlrev_b64 v[150:151], 12, v[200:201]
	flat_load_dwordx4 v[158:161], v[154:155]
	v_lshlrev_b64 v[154:155], 12, v[194:195]
	v_lshl_add_u64 v[146:147], v[226:227], 0, v[214:215]
	v_lshl_add_u64 v[150:151], v[226:227], 0, v[150:151]
	v_lshl_add_u64 v[154:155], v[226:227], 0, v[154:155]
	flat_load_dwordx4 v[146:149], v[146:147]
	s_waitcnt vmcnt(0) lgkmcnt(0)
	v_lshlrev_b32_e32 v156, 16, v159
	flat_load_dwordx4 v[150:153], v[150:151]
	v_and_b32_e32 v157, 0xffff0000, v159
	flat_load_dwordx4 v[182:185], v[154:155]
	v_lshlrev_b32_e32 v154, 16, v158
	v_lshlrev_b32_e32 v170, 16, v146
	v_and_b32_e32 v171, 0xffff0000, v146
	v_lshlrev_b32_e32 v172, 16, v147
	v_and_b32_e32 v173, 0xffff0000, v147
	v_lshlrev_b32_e32 v174, 16, v148
	v_and_b32_e32 v175, 0xffff0000, v148
	v_lshlrev_b32_e32 v176, 16, v149
	v_and_b32_e32 v177, 0xffff0000, v149
	v_and_b32_e32 v155, 0xffff0000, v158
	v_lshlrev_b32_e32 v158, 16, v160
	v_and_b32_e32 v159, 0xffff0000, v160
	v_lshlrev_b32_e32 v160, 16, v161
	v_and_b32_e32 v161, 0xffff0000, v161
	s_waitcnt vmcnt(0) lgkmcnt(0)
	v_lshlrev_b32_e32 v162, 16, v150
	v_and_b32_e32 v163, 0xffff0000, v150
	v_lshlrev_b32_e32 v164, 16, v151
	v_and_b32_e32 v165, 0xffff0000, v151
	v_lshlrev_b32_e32 v166, 16, v152
	v_and_b32_e32 v167, 0xffff0000, v152
	v_lshlrev_b32_e32 v168, 16, v153
	v_and_b32_e32 v169, 0xffff0000, v153
	v_lshlrev_b32_e32 v146, 16, v182
	v_and_b32_e32 v147, 0xffff0000, v182
	v_lshlrev_b32_e32 v148, 16, v183
	v_and_b32_e32 v149, 0xffff0000, v183
	v_lshlrev_b32_e32 v150, 16, v184
	v_and_b32_e32 v151, 0xffff0000, v184
	v_lshlrev_b32_e32 v152, 16, v185
	v_and_b32_e32 v153, 0xffff0000, v185
	s_cmp_lt_u32 s68, 2
	s_cbranch_scc1 .Lxr2_0
	v_rcp_f32_e32 v218, v218
	v_rcp_f32_e32 v219, v219
	v_rcp_f32_e32 v220, v220
	v_rcp_f32_e32 v221, v221
	v_rcp_f32_e32 v222, v222
	v_rcp_f32_e32 v223, v223
	v_rcp_f32_e32 v224, v224
	v_rcp_f32_e32 v225, v225
	s_nop 0
	v_pk_mul_f32 v[146:147], v[146:147], v[218:219]
	v_pk_mul_f32 v[148:149], v[148:149], v[220:221]
	v_pk_mul_f32 v[150:151], v[150:151], v[222:223]
	v_pk_mul_f32 v[152:153], v[152:153], v[224:225]
	v_pk_mul_f32 v[154:155], v[154:155], v[218:219]
	v_pk_mul_f32 v[156:157], v[156:157], v[220:221]
	v_pk_mul_f32 v[158:159], v[158:159], v[222:223]
	v_pk_mul_f32 v[160:161], v[160:161], v[224:225]
	v_pk_mul_f32 v[162:163], v[162:163], v[218:219]
	v_pk_mul_f32 v[164:165], v[164:165], v[220:221]
	v_pk_mul_f32 v[166:167], v[166:167], v[222:223]
	v_pk_mul_f32 v[168:169], v[168:169], v[224:225]
	v_pk_mul_f32 v[170:171], v[170:171], v[218:219]
	v_pk_mul_f32 v[172:173], v[172:173], v[220:221]
	v_pk_mul_f32 v[174:175], v[174:175], v[222:223]
	v_pk_mul_f32 v[176:177], v[176:177], v[224:225]
.Lxr2_0:
.LBB0_1058:
	v_lshlrev_b64 v[216:217], 11, v[178:179]
	v_lshl_add_u64 v[182:183], v[216:217], 0, v[196:197]
	s_waitcnt vmcnt(0) lgkmcnt(0)
	v_pk_fma_f32 v[192:193], v[142:143], v[110:111], v[170:171]
	v_lshlrev_b64 v[142:143], 1, v[182:183]
	v_pk_fma_f32 v[190:191], v[144:145], v[112:113], v[172:173]
	v_pk_fma_f32 v[174:175], v[138:139], v[106:107], v[174:175]
	v_cvt_pk_bf16_f32 v138, v192, v193
	v_cvt_pk_bf16_f32 v139, v190, v191
	v_lshl_add_u64 v[144:145], s[12:13], 0, v[142:143]
	v_pk_fma_f32 v[176:177], v[140:141], v[108:109], v[176:177]
	v_cvt_pk_bf16_f32 v140, v174, v175
	v_lshl_add_u64 v[142:143], s[18:19], 0, v[142:143]
	v_cvt_pk_bf16_f32 v141, v176, v177
	v_lshlrev_b64 v[218:219], 11, v[200:201]
	v_pk_mul_f32 v[144:145], v[100:101], v[176:177]
	v_pk_mul_f32 v[138:139], v[102:103], v[192:193]
	v_pk_mul_f32 v[140:141], v[104:105], v[190:191]
	v_cvt_pk_bf16_f32 v138, v138, v139
	v_pk_mul_f32 v[170:171], v[98:99], v[174:175]
	v_cvt_pk_bf16_f32 v139, v140, v141
	v_pk_fma_f32 v[172:173], v[134:135], v[110:111], v[162:163]
	v_cvt_pk_bf16_f32 v140, v170, v171
	v_cvt_pk_bf16_f32 v141, v144, v145
	flat_store_dwordx4 v[142:143], v[138:141]
	v_pk_fma_f32 v[170:171], v[136:137], v[112:113], v[164:165]
	v_pk_fma_f32 v[166:167], v[130:131], v[106:107], v[166:167]
	v_lshl_add_u64 v[138:139], v[218:219], 0, v[196:197]
	v_lshlrev_b64 v[134:135], 1, v[138:139]
	v_cvt_pk_bf16_f32 v130, v172, v173
	v_cvt_pk_bf16_f32 v131, v170, v171
	v_lshl_add_u64 v[136:137], s[12:13], 0, v[134:135]
	v_pk_fma_f32 v[168:169], v[132:133], v[108:109], v[168:169]
	v_cvt_pk_bf16_f32 v132, v166, v167
	v_lshl_add_u64 v[134:135], s[18:19], 0, v[134:135]
	v_cvt_pk_bf16_f32 v133, v168, v169
	v_lshlrev_b64 v[220:221], 11, v[198:199]
	v_pk_mul_f32 v[136:137], v[100:101], v[168:169]
	v_pk_mul_f32 v[130:131], v[102:103], v[172:173]
	v_pk_mul_f32 v[132:133], v[104:105], v[170:171]
	v_cvt_pk_bf16_f32 v130, v130, v131
	v_pk_mul_f32 v[138:139], v[98:99], v[166:167]
	v_cvt_pk_bf16_f32 v131, v132, v133
	v_pk_fma_f32 v[164:165], v[126:127], v[110:111], v[154:155]
	v_cvt_pk_bf16_f32 v132, v138, v139
	v_cvt_pk_bf16_f32 v133, v136, v137
	flat_store_dwordx4 v[134:135], v[130:133]
	v_pk_fma_f32 v[162:163], v[128:129], v[112:113], v[156:157]
	v_pk_fma_f32 v[158:159], v[122:123], v[106:107], v[158:159]
	v_lshl_add_u64 v[130:131], v[220:221], 0, v[196:197]
	v_lshlrev_b64 v[126:127], 1, v[130:131]
	v_cvt_pk_bf16_f32 v122, v164, v165
	v_cvt_pk_bf16_f32 v123, v162, v163
	v_lshl_add_u64 v[128:129], s[12:13], 0, v[126:127]
	v_pk_fma_f32 v[156:157], v[124:125], v[108:109], v[160:161]
	v_cvt_pk_bf16_f32 v124, v158, v159
	v_lshl_add_u64 v[126:127], s[18:19], 0, v[126:127]
	v_cvt_pk_bf16_f32 v125, v156, v157
	v_lshlrev_b64 v[222:223], 11, v[194:195]
	v_pk_mul_f32 v[128:129], v[100:101], v[156:157]
	v_pk_mul_f32 v[122:123], v[102:103], v[164:165]
	v_pk_mul_f32 v[124:125], v[104:105], v[162:163]
	v_cvt_pk_bf16_f32 v122, v122, v123
	v_pk_mul_f32 v[130:131], v[98:99], v[158:159]
	v_cvt_pk_bf16_f32 v123, v124, v125
	v_pk_fma_f32 v[154:155], v[118:119], v[110:111], v[146:147]
	v_cvt_pk_bf16_f32 v124, v130, v131
	v_cvt_pk_bf16_f32 v125, v128, v129
	flat_store_dwordx4 v[126:127], v[122:125]
	v_pk_fma_f32 v[146:147], v[116:117], v[108:109], v[152:153]
	v_add_u32_e32 v152, 0x80, v178
	v_lshl_add_u64 v[122:123], v[222:223], 0, v[196:197]
	v_lshlrev_b64 v[118:119], 1, v[122:123]
	v_pk_fma_f32 v[148:149], v[120:121], v[112:113], v[148:149]
	v_pk_fma_f32 v[150:151], v[114:115], v[106:107], v[150:151]
	v_cvt_pk_bf16_f32 v114, v154, v155
	v_cvt_pk_bf16_f32 v115, v148, v149
	v_lshl_add_u64 v[120:121], s[12:13], 0, v[118:119]
	v_cvt_pk_bf16_f32 v116, v150, v151
	v_cvt_pk_bf16_f32 v117, v146, v147
	v_ashrrev_i32_e32 v153, 31, v152
	v_lshl_add_u64 v[118:119], s[18:19], 0, v[118:119]
	s_and_b64 vcc, exec, s[8:9]
	v_pk_mul_f32 v[116:117], v[104:105], v[148:149]
	v_pk_mul_f32 v[114:115], v[102:103], v[154:155]
	v_lshlrev_b64 v[224:225], 13, v[152:153]
	v_add_u32_e32 v206, 0x90, v178
	v_add_u32_e32 v204, 0xa0, v178
	v_add_u32_e32 v202, 0xb0, v178
	v_pk_mul_f32 v[120:121], v[100:101], v[146:147]
	v_pk_mul_f32 v[122:123], v[98:99], v[150:151]
	v_cvt_pk_bf16_f32 v114, v114, v115
	v_cvt_pk_bf16_f32 v115, v116, v117
	s_nop 0
	v_cvt_pk_bf16_f32 v116, v122, v123
	v_cvt_pk_bf16_f32 v117, v120, v121
	flat_store_dwordx4 v[118:119], v[114:117]
	s_cbranch_vccnz .LBB0_1066
	s_nop 0
	v_lshl_add_u64 v[114:115], v[188:189], 0, v[224:225]
	v_ashrrev_i32_e32 v207, 31, v206
	global_load_dwordx4 v[142:145], v[114:115], off offset:16
	global_load_dwordx4 v[138:141], v[114:115], off
	v_lshlrev_b64 v[114:115], 13, v[206:207]
	v_lshl_add_u64 v[114:115], v[188:189], 0, v[114:115]
	v_ashrrev_i32_e32 v205, 31, v204
	global_load_dwordx4 v[134:137], v[114:115], off offset:16
	global_load_dwordx4 v[130:133], v[114:115], off
	v_lshlrev_b64 v[114:115], 13, v[204:205]
	v_lshl_add_u64 v[114:115], v[188:189], 0, v[114:115]
	v_ashrrev_i32_e32 v203, 31, v202
	global_load_dwordx4 v[126:129], v[114:115], off offset:16
	global_load_dwordx4 v[122:125], v[114:115], off
	v_lshlrev_b64 v[114:115], 13, v[202:203]
	v_lshl_add_u64 v[114:115], v[188:189], 0, v[114:115]
	global_load_dwordx4 v[118:121], v[114:115], off offset:16
	s_nop 0
	global_load_dwordx4 v[114:117], v[114:115], off
	v_lshlrev_b64 v[232:233], 12, v[152:153]
	s_cbranch_execnz .LBB0_1061
.LBB0_1060:
	v_ashrrev_i32_e32 v205, 31, v204
	s_waitcnt vmcnt(0)
	global_load_dwordx4 v[228:231], v[186:187], off
	global_load_dwordx2 v[234:235], v[186:187], off offset:16
	global_load_dwordx2 v[246:247], v[186:187], off offset:24
	v_lshlrev_b64 v[122:123], 12, v[204:205]
	v_ashrrev_i32_e32 v207, 31, v206
	v_lshl_add_u64 v[122:123], v[226:227], 0, v[122:123]
	v_ashrrev_i32_e32 v203, 31, v202
	v_lshlrev_b64 v[118:119], 12, v[206:207]
	flat_load_dwordx4 v[126:129], v[122:123]
	v_lshlrev_b64 v[122:123], 12, v[202:203]
	v_lshl_add_u64 v[114:115], v[226:227], 0, v[232:233]
	v_lshl_add_u64 v[118:119], v[226:227], 0, v[118:119]
	v_lshl_add_u64 v[122:123], v[226:227], 0, v[122:123]
	flat_load_dwordx4 v[114:117], v[114:115]
	s_waitcnt vmcnt(0) lgkmcnt(0)
	v_lshlrev_b32_e32 v124, 16, v127
	flat_load_dwordx4 v[118:121], v[118:119]
	v_and_b32_e32 v125, 0xffff0000, v127
	flat_load_dwordx4 v[182:185], v[122:123]
	v_lshlrev_b32_e32 v122, 16, v126
	v_lshlrev_b32_e32 v138, 16, v114
	v_and_b32_e32 v139, 0xffff0000, v114
	v_lshlrev_b32_e32 v140, 16, v115
	v_and_b32_e32 v141, 0xffff0000, v115
	v_lshlrev_b32_e32 v142, 16, v116
	v_and_b32_e32 v143, 0xffff0000, v116
	v_lshlrev_b32_e32 v144, 16, v117
	v_and_b32_e32 v145, 0xffff0000, v117
	v_and_b32_e32 v123, 0xffff0000, v126
	v_lshlrev_b32_e32 v126, 16, v128
	v_and_b32_e32 v127, 0xffff0000, v128
	v_lshlrev_b32_e32 v128, 16, v129
	v_and_b32_e32 v129, 0xffff0000, v129
	s_waitcnt vmcnt(0) lgkmcnt(0)
	v_lshlrev_b32_e32 v130, 16, v118
	v_and_b32_e32 v131, 0xffff0000, v118
	v_lshlrev_b32_e32 v132, 16, v119
	v_and_b32_e32 v133, 0xffff0000, v119
	v_lshlrev_b32_e32 v134, 16, v120
	v_and_b32_e32 v135, 0xffff0000, v120
	v_lshlrev_b32_e32 v136, 16, v121
	v_and_b32_e32 v137, 0xffff0000, v121
	v_lshlrev_b32_e32 v114, 16, v182
	v_and_b32_e32 v115, 0xffff0000, v182
	v_lshlrev_b32_e32 v116, 16, v183
	v_and_b32_e32 v117, 0xffff0000, v183
	v_lshlrev_b32_e32 v118, 16, v184
	v_and_b32_e32 v119, 0xffff0000, v184
	v_lshlrev_b32_e32 v120, 16, v185
	v_and_b32_e32 v121, 0xffff0000, v185
	s_cmp_lt_u32 s68, 2
	s_cbranch_scc1 .Lxr2_1
	v_rcp_f32_e32 v228, v228
	v_rcp_f32_e32 v229, v229
	v_rcp_f32_e32 v230, v230
	v_rcp_f32_e32 v231, v231
	v_rcp_f32_e32 v234, v234
	v_rcp_f32_e32 v235, v235
	v_rcp_f32_e32 v246, v246
	v_rcp_f32_e32 v247, v247
	s_nop 0
	v_pk_mul_f32 v[114:115], v[114:115], v[228:229]
	v_pk_mul_f32 v[116:117], v[116:117], v[230:231]
	v_pk_mul_f32 v[118:119], v[118:119], v[234:235]
	v_pk_mul_f32 v[120:121], v[120:121], v[246:247]
	v_pk_mul_f32 v[122:123], v[122:123], v[228:229]
	v_pk_mul_f32 v[124:125], v[124:125], v[230:231]
	v_pk_mul_f32 v[126:127], v[126:127], v[234:235]
	v_pk_mul_f32 v[128:129], v[128:129], v[246:247]
	v_pk_mul_f32 v[130:131], v[130:131], v[228:229]
	v_pk_mul_f32 v[132:133], v[132:133], v[230:231]
	v_pk_mul_f32 v[134:135], v[134:135], v[234:235]
	v_pk_mul_f32 v[136:137], v[136:137], v[246:247]
	v_pk_mul_f32 v[138:139], v[138:139], v[228:229]
	v_pk_mul_f32 v[140:141], v[140:141], v[230:231]
	v_pk_mul_f32 v[142:143], v[142:143], v[234:235]
	v_pk_mul_f32 v[144:145], v[144:145], v[246:247]
.Lxr2_1:
.LBB0_1061:
	v_lshlrev_b64 v[226:227], 11, v[152:153]
	v_lshl_add_u64 v[160:161], v[226:227], 0, v[196:197]
	s_waitcnt vmcnt(0)
	v_pk_fma_f32 v[152:153], v[94:95], v[110:111], v[138:139]
	v_lshlrev_b64 v[94:95], 1, v[160:161]
	v_pk_fma_f32 v[140:141], v[96:97], v[112:113], v[140:141]
	v_pk_fma_f32 v[138:139], v[92:93], v[108:109], v[144:145]
	v_pk_fma_f32 v[144:145], v[90:91], v[106:107], v[142:143]
	v_cvt_pk_bf16_f32 v90, v152, v153
	v_cvt_pk_bf16_f32 v91, v140, v141
	v_lshl_add_u64 v[96:97], s[12:13], 0, v[94:95]
	v_cvt_pk_bf16_f32 v92, v144, v145
	v_cvt_pk_bf16_f32 v93, v138, v139
	v_lshl_add_u64 v[94:95], s[18:19], 0, v[94:95]
	v_lshlrev_b64 v[228:229], 11, v[206:207]
	v_pk_mul_f32 v[90:91], v[102:103], v[152:153]
	v_pk_mul_f32 v[92:93], v[104:105], v[140:141]
	v_cvt_pk_bf16_f32 v90, v90, v91
	v_pk_mul_f32 v[96:97], v[100:101], v[138:139]
	v_cvt_pk_bf16_f32 v91, v92, v93
	v_pk_mul_f32 v[142:143], v[98:99], v[144:145]
	v_pk_fma_f32 v[160:161], v[86:87], v[110:111], v[130:131]
	v_cvt_pk_bf16_f32 v92, v142, v143
	v_cvt_pk_bf16_f32 v93, v96, v97
	flat_store_dwordx4 v[94:95], v[90:93]
	v_pk_fma_f32 v[142:143], v[88:89], v[112:113], v[132:133]
	v_pk_fma_f32 v[134:135], v[82:83], v[106:107], v[134:135]
	v_lshl_add_u64 v[90:91], v[228:229], 0, v[196:197]
	v_lshlrev_b64 v[86:87], 1, v[90:91]
	v_cvt_pk_bf16_f32 v82, v160, v161
	v_cvt_pk_bf16_f32 v83, v142, v143
	v_lshl_add_u64 v[88:89], s[12:13], 0, v[86:87]
	v_pk_fma_f32 v[136:137], v[84:85], v[108:109], v[136:137]
	v_cvt_pk_bf16_f32 v84, v134, v135
	v_lshl_add_u64 v[86:87], s[18:19], 0, v[86:87]
	v_cvt_pk_bf16_f32 v85, v136, v137
	v_lshlrev_b64 v[230:231], 11, v[204:205]
	v_pk_mul_f32 v[88:89], v[100:101], v[136:137]
	v_pk_mul_f32 v[82:83], v[102:103], v[160:161]
	v_pk_mul_f32 v[84:85], v[104:105], v[142:143]
	v_cvt_pk_bf16_f32 v82, v82, v83
	v_pk_mul_f32 v[90:91], v[98:99], v[134:135]
	v_cvt_pk_bf16_f32 v83, v84, v85
	v_pk_fma_f32 v[132:133], v[78:79], v[110:111], v[122:123]
	v_cvt_pk_bf16_f32 v84, v90, v91
	v_cvt_pk_bf16_f32 v85, v88, v89
	flat_store_dwordx4 v[86:87], v[82:85]
	v_pk_fma_f32 v[130:131], v[80:81], v[112:113], v[124:125]
	v_pk_fma_f32 v[126:127], v[74:75], v[106:107], v[126:127]
	v_lshl_add_u64 v[82:83], v[230:231], 0, v[196:197]
	v_lshlrev_b64 v[78:79], 1, v[82:83]
	v_cvt_pk_bf16_f32 v74, v132, v133
	v_cvt_pk_bf16_f32 v75, v130, v131
	v_lshl_add_u64 v[80:81], s[12:13], 0, v[78:79]
	v_pk_fma_f32 v[124:125], v[76:77], v[108:109], v[128:129]
	v_cvt_pk_bf16_f32 v76, v126, v127
	v_lshl_add_u64 v[78:79], s[18:19], 0, v[78:79]
	v_cvt_pk_bf16_f32 v77, v124, v125
	v_lshlrev_b64 v[128:129], 11, v[202:203]
	v_pk_mul_f32 v[80:81], v[100:101], v[124:125]
	v_pk_mul_f32 v[74:75], v[102:103], v[132:133]
	v_pk_mul_f32 v[76:77], v[104:105], v[130:131]
	v_cvt_pk_bf16_f32 v74, v74, v75
	v_pk_mul_f32 v[82:83], v[98:99], v[126:127]
	v_cvt_pk_bf16_f32 v75, v76, v77
	v_pk_fma_f32 v[122:123], v[70:71], v[110:111], v[114:115]
	v_cvt_pk_bf16_f32 v76, v82, v83
	v_cvt_pk_bf16_f32 v77, v80, v81
	flat_store_dwordx4 v[78:79], v[74:77]
	v_pk_fma_f32 v[116:117], v[72:73], v[112:113], v[116:117]
	v_pk_fma_f32 v[114:115], v[68:69], v[108:109], v[120:121]
	v_lshl_add_u64 v[74:75], v[128:129], 0, v[196:197]
	v_lshlrev_b64 v[70:71], 1, v[74:75]
	v_pk_fma_f32 v[118:119], v[66:67], v[106:107], v[118:119]
	v_cvt_pk_bf16_f32 v66, v122, v123
	v_cvt_pk_bf16_f32 v67, v116, v117
	v_lshl_add_u64 v[72:73], s[12:13], 0, v[70:71]
	v_cvt_pk_bf16_f32 v68, v118, v119
	v_cvt_pk_bf16_f32 v69, v114, v115
	v_lshl_add_u64 v[70:71], s[18:19], 0, v[70:71]
	v_pk_mul_f32 v[72:73], v[100:101], v[114:115]
	v_pk_mul_f32 v[68:69], v[104:105], v[116:117]
	v_pk_mul_f32 v[66:67], v[102:103], v[122:123]
	v_pk_mul_f32 v[74:75], v[98:99], v[118:119]
	v_cvt_pk_bf16_f32 v66, v66, v67
	v_cvt_pk_bf16_f32 v67, v68, v69
	s_and_b64 vcc, exec, s[8:9]
	v_cvt_pk_bf16_f32 v68, v74, v75
	v_cvt_pk_bf16_f32 v69, v72, v73
	flat_store_dwordx4 v[70:71], v[66:69]
	flat_load_dwordx4 v[78:81], v[208:209] offset:512
	flat_load_dwordx4 v[74:77], v[208:209] offset:528
	s_nop 0
	flat_load_dwordx4 v[70:73], v[210:211] offset:512
	flat_load_dwordx4 v[66:69], v[210:211] offset:528
	s_cbranch_vccnz .LBB0_1067
	v_lshl_add_u64 v[82:83], v[188:189], 0, v[212:213]
	global_load_dwordx4 v[110:113], v[82:83], off offset:528
	global_load_dwordx4 v[106:109], v[82:83], off offset:512
	v_lshlrev_b64 v[82:83], 13, v[200:201]
	v_lshl_add_u64 v[82:83], v[188:189], 0, v[82:83]
	global_load_dwordx4 v[102:105], v[82:83], off offset:528
	global_load_dwordx4 v[98:101], v[82:83], off offset:512
	v_lshlrev_b64 v[82:83], 13, v[198:199]
	v_lshl_add_u64 v[82:83], v[188:189], 0, v[82:83]
	global_load_dwordx4 v[94:97], v[82:83], off offset:528
	global_load_dwordx4 v[90:93], v[82:83], off offset:512
	v_lshlrev_b64 v[82:83], 13, v[194:195]
	v_lshl_add_u64 v[82:83], v[188:189], 0, v[82:83]
	global_load_dwordx4 v[86:89], v[82:83], off offset:528
	s_nop 0
	global_load_dwordx4 v[82:85], v[82:83], off offset:512
	s_mov_b64 s[30:31], 0
	s_branch .LBB0_1068

.LBB0_1068:
	v_or_b32_e32 v120, 0x80, v196
	v_ashrrev_i32_e32 v121, 31, v120
	s_andn2_b64 vcc, exec, s[30:31]
	v_lshlrev_b64 v[196:197], 1, v[120:121]
	s_cbranch_vccnz .LBB0_1070
	s_waitcnt vmcnt(0)
	global_load_dwordx4 v[208:211], v[186:187], off offset:512
	global_load_dwordx2 v[212:213], v[186:187], off offset:528
	global_load_dwordx2 v[234:235], v[186:187], off offset:536
	v_lshlrev_b64 v[90:91], 12, v[198:199]
	v_lshl_add_u64 v[90:91], s[12:13], 0, v[90:91]
	v_lshl_add_u64 v[90:91], v[90:91], 0, v[196:197]
	v_lshlrev_b64 v[86:87], 12, v[200:201]
	flat_load_dwordx4 v[94:97], v[90:91]
	v_lshlrev_b64 v[90:91], 12, v[194:195]
	v_lshl_add_u64 v[82:83], s[12:13], 0, v[214:215]
	v_lshl_add_u64 v[86:87], s[12:13], 0, v[86:87]
	v_lshl_add_u64 v[90:91], s[12:13], 0, v[90:91]
	v_lshl_add_u64 v[82:83], v[82:83], 0, v[196:197]
	v_lshl_add_u64 v[86:87], v[86:87], 0, v[196:197]
	v_lshl_add_u64 v[90:91], v[90:91], 0, v[196:197]
	flat_load_dwordx4 v[82:85], v[82:83]
	s_waitcnt vmcnt(0) lgkmcnt(0)
	v_lshlrev_b32_e32 v92, 16, v95
	flat_load_dwordx4 v[86:89], v[86:87]
	v_and_b32_e32 v93, 0xffff0000, v95
	flat_load_dwordx4 v[182:185], v[90:91]
	v_lshlrev_b32_e32 v90, 16, v94
	v_and_b32_e32 v91, 0xffff0000, v94
	v_lshlrev_b32_e32 v94, 16, v96
	v_and_b32_e32 v95, 0xffff0000, v96
	v_lshlrev_b32_e32 v106, 16, v82
	v_and_b32_e32 v107, 0xffff0000, v82
	v_lshlrev_b32_e32 v108, 16, v83
	v_and_b32_e32 v109, 0xffff0000, v83
	v_lshlrev_b32_e32 v110, 16, v84
	v_and_b32_e32 v111, 0xffff0000, v84
	v_lshlrev_b32_e32 v112, 16, v85
	v_and_b32_e32 v113, 0xffff0000, v85
	v_lshlrev_b32_e32 v96, 16, v97
	v_and_b32_e32 v97, 0xffff0000, v97
	s_waitcnt vmcnt(0) lgkmcnt(0)
	v_lshlrev_b32_e32 v98, 16, v86
	v_and_b32_e32 v99, 0xffff0000, v86
	v_lshlrev_b32_e32 v100, 16, v87
	v_and_b32_e32 v101, 0xffff0000, v87
	v_lshlrev_b32_e32 v102, 16, v88
	v_and_b32_e32 v103, 0xffff0000, v88
	v_lshlrev_b32_e32 v104, 16, v89
	v_and_b32_e32 v105, 0xffff0000, v89
	v_lshlrev_b32_e32 v82, 16, v182
	v_and_b32_e32 v83, 0xffff0000, v182
	v_lshlrev_b32_e32 v84, 16, v183
	v_and_b32_e32 v85, 0xffff0000, v183
	v_lshlrev_b32_e32 v86, 16, v184
	v_and_b32_e32 v87, 0xffff0000, v184
	v_lshlrev_b32_e32 v88, 16, v185
	v_and_b32_e32 v89, 0xffff0000, v185
	s_cmp_lt_u32 s68, 2
	s_cbranch_scc1 .Lxr2_2
	v_rcp_f32_e32 v208, v208
	v_rcp_f32_e32 v209, v209
	v_rcp_f32_e32 v210, v210
	v_rcp_f32_e32 v211, v211
	v_rcp_f32_e32 v212, v212
	v_rcp_f32_e32 v213, v213
	v_rcp_f32_e32 v234, v234
	v_rcp_f32_e32 v235, v235
	s_nop 0
	v_pk_mul_f32 v[82:83], v[82:83], v[208:209]
	v_pk_mul_f32 v[84:85], v[84:85], v[210:211]
	v_pk_mul_f32 v[86:87], v[86:87], v[212:213]
	v_pk_mul_f32 v[88:89], v[88:89], v[234:235]
	v_pk_mul_f32 v[90:91], v[90:91], v[208:209]
	v_pk_mul_f32 v[92:93], v[92:93], v[210:211]
	v_pk_mul_f32 v[94:95], v[94:95], v[212:213]
	v_pk_mul_f32 v[96:97], v[96:97], v[234:235]
	v_pk_mul_f32 v[98:99], v[98:99], v[208:209]
	v_pk_mul_f32 v[100:101], v[100:101], v[210:211]
	v_pk_mul_f32 v[102:103], v[102:103], v[212:213]
	v_pk_mul_f32 v[104:105], v[104:105], v[234:235]
	v_pk_mul_f32 v[106:107], v[106:107], v[208:209]
	v_pk_mul_f32 v[108:109], v[108:109], v[210:211]
	v_pk_mul_f32 v[110:111], v[110:111], v[212:213]
	v_pk_mul_f32 v[112:113], v[112:113], v[234:235]
.Lxr2_2:
.LBB0_1070:
	v_lshl_add_u64 v[182:183], v[216:217], 0, v[120:121]
	s_waitcnt vmcnt(0) lgkmcnt(0)
	v_pk_fma_f32 v[198:199], v[62:63], v[78:79], v[106:107]
	v_lshlrev_b64 v[62:63], 1, v[182:183]
	v_pk_fma_f32 v[194:195], v[64:65], v[80:81], v[108:109]
	v_pk_fma_f32 v[110:111], v[58:59], v[74:75], v[110:111]
	v_cvt_pk_bf16_f32 v58, v198, v199
	v_cvt_pk_bf16_f32 v59, v194, v195
	v_lshl_add_u64 v[64:65], s[12:13], 0, v[62:63]
	v_pk_fma_f32 v[112:113], v[60:61], v[76:77], v[112:113]
	v_cvt_pk_bf16_f32 v60, v110, v111
	v_lshl_add_u64 v[62:63], s[18:19], 0, v[62:63]
	v_cvt_pk_bf16_f32 v61, v112, v113
	v_pk_mul_f32 v[64:65], v[68:69], v[112:113]
	v_pk_mul_f32 v[106:107], v[66:67], v[110:111]
	v_pk_mul_f32 v[58:59], v[70:71], v[198:199]
	v_pk_mul_f32 v[60:61], v[72:73], v[194:195]
	v_cvt_pk_bf16_f32 v58, v58, v59
	v_pk_fma_f32 v[108:109], v[54:55], v[78:79], v[98:99]
	v_cvt_pk_bf16_f32 v59, v60, v61
	v_cvt_pk_bf16_f32 v60, v106, v107
	v_cvt_pk_bf16_f32 v61, v64, v65
	flat_store_dwordx4 v[62:63], v[58:61]
	v_pk_fma_f32 v[106:107], v[56:57], v[80:81], v[100:101]
	v_pk_fma_f32 v[102:103], v[50:51], v[74:75], v[102:103]
	v_lshl_add_u64 v[58:59], v[218:219], 0, v[120:121]
	v_lshlrev_b64 v[54:55], 1, v[58:59]
	v_cvt_pk_bf16_f32 v50, v108, v109
	v_cvt_pk_bf16_f32 v51, v106, v107
	v_lshl_add_u64 v[56:57], s[12:13], 0, v[54:55]
	v_pk_fma_f32 v[104:105], v[52:53], v[76:77], v[104:105]
	v_cvt_pk_bf16_f32 v52, v102, v103
	v_lshl_add_u64 v[54:55], s[18:19], 0, v[54:55]
	v_cvt_pk_bf16_f32 v53, v104, v105
	v_pk_mul_f32 v[56:57], v[68:69], v[104:105]
	v_pk_mul_f32 v[58:59], v[66:67], v[102:103]
	v_pk_mul_f32 v[50:51], v[70:71], v[108:109]
	v_pk_mul_f32 v[52:53], v[72:73], v[106:107]
	v_cvt_pk_bf16_f32 v50, v50, v51
	v_pk_fma_f32 v[100:101], v[46:47], v[78:79], v[90:91]
	v_cvt_pk_bf16_f32 v51, v52, v53
	v_cvt_pk_bf16_f32 v52, v58, v59
	v_cvt_pk_bf16_f32 v53, v56, v57
	flat_store_dwordx4 v[54:55], v[50:53]
	v_pk_fma_f32 v[98:99], v[48:49], v[80:81], v[92:93]
	v_pk_fma_f32 v[94:95], v[42:43], v[74:75], v[94:95]
	v_lshl_add_u64 v[50:51], v[220:221], 0, v[120:121]
	v_lshlrev_b64 v[46:47], 1, v[50:51]
	v_cvt_pk_bf16_f32 v42, v100, v101
	v_cvt_pk_bf16_f32 v43, v98, v99
	v_lshl_add_u64 v[48:49], s[12:13], 0, v[46:47]
	v_pk_fma_f32 v[92:93], v[44:45], v[76:77], v[96:97]
	v_cvt_pk_bf16_f32 v44, v94, v95
	v_lshl_add_u64 v[46:47], s[18:19], 0, v[46:47]
	v_cvt_pk_bf16_f32 v45, v92, v93
	v_pk_mul_f32 v[48:49], v[68:69], v[92:93]
	v_pk_mul_f32 v[50:51], v[66:67], v[94:95]
	v_pk_mul_f32 v[42:43], v[70:71], v[100:101]
	v_pk_mul_f32 v[44:45], v[72:73], v[98:99]
	v_cvt_pk_bf16_f32 v42, v42, v43
	v_pk_fma_f32 v[90:91], v[38:39], v[78:79], v[82:83]
	v_cvt_pk_bf16_f32 v43, v44, v45
	v_cvt_pk_bf16_f32 v44, v50, v51
	v_cvt_pk_bf16_f32 v45, v48, v49
	flat_store_dwordx4 v[46:47], v[42:45]
	v_pk_fma_f32 v[84:85], v[40:41], v[80:81], v[84:85]
	v_pk_fma_f32 v[82:83], v[36:37], v[76:77], v[88:89]
	v_lshl_add_u64 v[42:43], v[222:223], 0, v[120:121]
	v_lshlrev_b64 v[38:39], 1, v[42:43]
	v_pk_fma_f32 v[86:87], v[34:35], v[74:75], v[86:87]
	v_cvt_pk_bf16_f32 v34, v90, v91
	v_cvt_pk_bf16_f32 v35, v84, v85
	v_lshl_add_u64 v[40:41], s[12:13], 0, v[38:39]
	v_cvt_pk_bf16_f32 v36, v86, v87
	v_cvt_pk_bf16_f32 v37, v82, v83
	v_lshl_add_u64 v[38:39], s[18:19], 0, v[38:39]
	s_and_b64 vcc, exec, s[8:9]
	v_pk_mul_f32 v[36:37], v[72:73], v[84:85]
	v_pk_mul_f32 v[34:35], v[70:71], v[90:91]
	v_pk_mul_f32 v[40:41], v[68:69], v[82:83]
	v_pk_mul_f32 v[42:43], v[66:67], v[86:87]
	v_cvt_pk_bf16_f32 v34, v34, v35
	v_cvt_pk_bf16_f32 v35, v36, v37
	s_nop 0
	v_cvt_pk_bf16_f32 v36, v42, v43
	v_cvt_pk_bf16_f32 v37, v40, v41
	flat_store_dwordx4 v[38:39], v[34:37]
	s_cbranch_vccnz .LBB0_1092
	s_nop 0
	v_lshl_add_u64 v[34:35], v[188:189], 0, v[224:225]
	global_load_dwordx4 v[62:65], v[34:35], off offset:528
	global_load_dwordx4 v[58:61], v[34:35], off offset:512
	v_lshlrev_b64 v[34:35], 13, v[206:207]
	v_lshl_add_u64 v[34:35], v[188:189], 0, v[34:35]
	global_load_dwordx4 v[54:57], v[34:35], off offset:528
	global_load_dwordx4 v[50:53], v[34:35], off offset:512
	v_lshlrev_b64 v[34:35], 13, v[204:205]
	v_lshl_add_u64 v[34:35], v[188:189], 0, v[34:35]
	global_load_dwordx4 v[46:49], v[34:35], off offset:528
	global_load_dwordx4 v[42:45], v[34:35], off offset:512
	v_lshlrev_b64 v[34:35], 13, v[202:203]
	v_lshl_add_u64 v[34:35], v[188:189], 0, v[34:35]
	global_load_dwordx4 v[38:41], v[34:35], off offset:528
	s_nop 0
	global_load_dwordx4 v[34:37], v[34:35], off offset:512
	s_cbranch_execnz .LBB0_1073
.LBB0_1072:
	s_waitcnt vmcnt(0)
	global_load_dwordx4 v[208:211], v[186:187], off offset:512
	global_load_dwordx4 v[212:215], v[186:187], off offset:528
	v_lshlrev_b64 v[42:43], 12, v[204:205]
	v_lshl_add_u64 v[42:43], s[12:13], 0, v[42:43]
	v_lshl_add_u64 v[42:43], v[42:43], 0, v[196:197]
	v_lshlrev_b64 v[38:39], 12, v[206:207]
	flat_load_dwordx4 v[46:49], v[42:43]
	v_lshlrev_b64 v[42:43], 12, v[202:203]
	v_lshl_add_u64 v[34:35], s[12:13], 0, v[232:233]
	v_lshl_add_u64 v[38:39], s[12:13], 0, v[38:39]
	v_lshl_add_u64 v[42:43], s[12:13], 0, v[42:43]
	v_lshl_add_u64 v[34:35], v[34:35], 0, v[196:197]
	v_lshl_add_u64 v[38:39], v[38:39], 0, v[196:197]
	v_lshl_add_u64 v[42:43], v[42:43], 0, v[196:197]
	flat_load_dwordx4 v[34:37], v[34:35]
	s_waitcnt vmcnt(0) lgkmcnt(0)
	v_lshlrev_b32_e32 v44, 16, v47
	flat_load_dwordx4 v[38:41], v[38:39]
	v_and_b32_e32 v45, 0xffff0000, v47
	flat_load_dwordx4 v[182:185], v[42:43]
	v_lshlrev_b32_e32 v42, 16, v46
	v_and_b32_e32 v43, 0xffff0000, v46
	v_lshlrev_b32_e32 v46, 16, v48
	v_and_b32_e32 v47, 0xffff0000, v48
	v_lshlrev_b32_e32 v58, 16, v34
	v_and_b32_e32 v59, 0xffff0000, v34
	v_lshlrev_b32_e32 v60, 16, v35
	v_and_b32_e32 v61, 0xffff0000, v35
	v_lshlrev_b32_e32 v62, 16, v36
	v_and_b32_e32 v63, 0xffff0000, v36
	v_lshlrev_b32_e32 v64, 16, v37
	v_and_b32_e32 v65, 0xffff0000, v37
	v_lshlrev_b32_e32 v48, 16, v49
	v_and_b32_e32 v49, 0xffff0000, v49
	s_waitcnt vmcnt(0) lgkmcnt(0)
	v_lshlrev_b32_e32 v50, 16, v38
	v_and_b32_e32 v51, 0xffff0000, v38
	v_lshlrev_b32_e32 v52, 16, v39
	v_and_b32_e32 v53, 0xffff0000, v39
	v_lshlrev_b32_e32 v54, 16, v40
	v_and_b32_e32 v55, 0xffff0000, v40
	v_lshlrev_b32_e32 v56, 16, v41
	v_and_b32_e32 v57, 0xffff0000, v41
	v_lshlrev_b32_e32 v34, 16, v182
	v_and_b32_e32 v35, 0xffff0000, v182
	v_lshlrev_b32_e32 v36, 16, v183
	v_and_b32_e32 v37, 0xffff0000, v183
	v_lshlrev_b32_e32 v38, 16, v184
	v_and_b32_e32 v39, 0xffff0000, v184
	v_lshlrev_b32_e32 v40, 16, v185
	v_and_b32_e32 v41, 0xffff0000, v185
	s_cmp_lt_u32 s68, 2
	s_cbranch_scc1 .Lxr2_3
	v_rcp_f32_e32 v208, v208
	v_rcp_f32_e32 v209, v209
	v_rcp_f32_e32 v210, v210
	v_rcp_f32_e32 v211, v211
	v_rcp_f32_e32 v212, v212
	v_rcp_f32_e32 v213, v213
	v_rcp_f32_e32 v214, v214
	v_rcp_f32_e32 v215, v215
	s_nop 0
	v_pk_mul_f32 v[34:35], v[34:35], v[208:209]
	v_pk_mul_f32 v[36:37], v[36:37], v[210:211]
	v_pk_mul_f32 v[38:39], v[38:39], v[212:213]
	v_pk_mul_f32 v[40:41], v[40:41], v[214:215]
	v_pk_mul_f32 v[42:43], v[42:43], v[208:209]
	v_pk_mul_f32 v[44:45], v[44:45], v[210:211]
	v_pk_mul_f32 v[46:47], v[46:47], v[212:213]
	v_pk_mul_f32 v[48:49], v[48:49], v[214:215]
	v_pk_mul_f32 v[50:51], v[50:51], v[208:209]
	v_pk_mul_f32 v[52:53], v[52:53], v[210:211]
	v_pk_mul_f32 v[54:55], v[54:55], v[212:213]
	v_pk_mul_f32 v[56:57], v[56:57], v[214:215]
	v_pk_mul_f32 v[58:59], v[58:59], v[208:209]
	v_pk_mul_f32 v[60:61], v[60:61], v[210:211]
	v_pk_mul_f32 v[62:63], v[62:63], v[212:213]
	v_pk_mul_f32 v[64:65], v[64:65], v[214:215]
.Lxr2_3:
.LBB0_1073:
	v_mul_f32_e32 v88, v192, v192
	v_mul_f32_e32 v89, v190, v190
	v_fmac_f32_e32 v88, v193, v193
	v_fmac_f32_e32 v89, v191, v191
	v_add_f32_e32 v88, v89, v88
	v_mul_f32_e32 v89, v174, v174
	v_mul_f32_e32 v96, v177, v177
	v_fmac_f32_e32 v89, v175, v175
	v_fmac_f32_e32 v96, v176, v176
	v_add_f32_e32 v89, v96, v89
	v_add_f32_e32 v88, v89, v88
	v_mul_f32_e32 v89, v198, v198
	v_mul_f32_e32 v96, v194, v194
	v_fmac_f32_e32 v89, v199, v199
	v_fmac_f32_e32 v96, v195, v195
	v_add_f32_e32 v89, v96, v89
	v_mul_f32_e32 v96, v110, v110
	v_mul_f32_e32 v97, v113, v113
	v_fmac_f32_e32 v96, v111, v111
	v_fmac_f32_e32 v97, v112, v112
	v_add_f32_e32 v96, v97, v96
	v_add_f32_e32 v89, v96, v89
	v_add_f32_e32 v96, v88, v89
	v_lshl_add_u64 v[88:89], v[226:227], 0, v[120:121]
	s_waitcnt vmcnt(0)
	v_pk_fma_f32 v[26:27], v[26:27], v[74:75], v[62:63]
	v_lshlrev_b64 v[62:63], 1, v[88:89]
	v_pk_fma_f32 v[32:33], v[32:33], v[80:81], v[60:61]
	v_pk_fma_f32 v[30:31], v[30:31], v[78:79], v[58:59]
	v_pk_fma_f32 v[28:29], v[28:29], v[76:77], v[64:65]
	v_cvt_pk_bf16_f32 v58, v30, v31
	v_cvt_pk_bf16_f32 v59, v32, v33
	v_lshl_add_u64 v[64:65], s[12:13], 0, v[62:63]
	v_cvt_pk_bf16_f32 v60, v26, v27
	v_cvt_pk_bf16_f32 v61, v28, v29
	v_lshl_add_u64 v[62:63], s[18:19], 0, v[62:63]
	v_pk_mul_f32 v[64:65], v[68:69], v[28:29]
	v_pk_mul_f32 v[58:59], v[70:71], v[30:31]
	v_pk_mul_f32 v[60:61], v[72:73], v[32:33]
	v_cvt_pk_bf16_f32 v58, v58, v59
	v_pk_mul_f32 v[88:89], v[66:67], v[26:27]
	v_cvt_pk_bf16_f32 v59, v60, v61
	v_pk_fma_f32 v[18:19], v[18:19], v[74:75], v[54:55]
	v_cvt_pk_bf16_f32 v60, v88, v89
	v_cvt_pk_bf16_f32 v61, v64, v65
	flat_store_dwordx4 v[62:63], v[58:61]
	v_pk_fma_f32 v[24:25], v[24:25], v[80:81], v[52:53]
	v_pk_fma_f32 v[22:23], v[22:23], v[78:79], v[50:51]
	v_lshl_add_u64 v[58:59], v[228:229], 0, v[120:121]
	v_lshlrev_b64 v[54:55], 1, v[58:59]
	v_pk_fma_f32 v[20:21], v[20:21], v[76:77], v[56:57]
	v_cvt_pk_bf16_f32 v50, v22, v23
	v_cvt_pk_bf16_f32 v51, v24, v25
	v_lshl_add_u64 v[56:57], s[12:13], 0, v[54:55]
	v_cvt_pk_bf16_f32 v52, v18, v19
	v_cvt_pk_bf16_f32 v53, v20, v21
	v_lshl_add_u64 v[54:55], s[18:19], 0, v[54:55]
	v_pk_mul_f32 v[56:57], v[68:69], v[20:21]
	v_pk_mul_f32 v[50:51], v[70:71], v[22:23]
	v_pk_mul_f32 v[52:53], v[72:73], v[24:25]
	v_cvt_pk_bf16_f32 v50, v50, v51
	v_pk_mul_f32 v[58:59], v[66:67], v[18:19]
	v_cvt_pk_bf16_f32 v51, v52, v53
	v_pk_fma_f32 v[10:11], v[10:11], v[74:75], v[46:47]
	v_cvt_pk_bf16_f32 v52, v58, v59
	v_cvt_pk_bf16_f32 v53, v56, v57
	flat_store_dwordx4 v[54:55], v[50:53]
	v_pk_fma_f32 v[16:17], v[16:17], v[80:81], v[44:45]
	v_pk_fma_f32 v[14:15], v[14:15], v[78:79], v[42:43]
	v_lshl_add_u64 v[50:51], v[230:231], 0, v[120:121]
	v_lshlrev_b64 v[46:47], 1, v[50:51]
	v_pk_fma_f32 v[12:13], v[12:13], v[76:77], v[48:49]
	v_cvt_pk_bf16_f32 v42, v14, v15
	v_cvt_pk_bf16_f32 v43, v16, v17
	v_lshl_add_u64 v[48:49], s[12:13], 0, v[46:47]
	v_cvt_pk_bf16_f32 v44, v10, v11
	v_cvt_pk_bf16_f32 v45, v12, v13
	v_lshl_add_u64 v[46:47], s[18:19], 0, v[46:47]
	v_pk_mul_f32 v[48:49], v[68:69], v[12:13]
	v_pk_mul_f32 v[42:43], v[70:71], v[14:15]
	v_pk_mul_f32 v[44:45], v[72:73], v[16:17]
	v_cvt_pk_bf16_f32 v42, v42, v43
	v_pk_mul_f32 v[50:51], v[66:67], v[10:11]
	v_cvt_pk_bf16_f32 v43, v44, v45
	v_pk_fma_f32 v[2:3], v[2:3], v[74:75], v[38:39]
	v_cvt_pk_bf16_f32 v44, v50, v51
	v_cvt_pk_bf16_f32 v45, v48, v49
	flat_store_dwordx4 v[46:47], v[42:45]
	v_pk_fma_f32 v[8:9], v[8:9], v[80:81], v[36:37]
	v_pk_fma_f32 v[6:7], v[6:7], v[78:79], v[34:35]
	v_lshl_add_u64 v[42:43], v[128:129], 0, v[120:121]
	v_lshlrev_b64 v[38:39], 1, v[42:43]
	v_pk_fma_f32 v[4:5], v[4:5], v[76:77], v[40:41]
	v_cvt_pk_bf16_f32 v34, v6, v7
	v_cvt_pk_bf16_f32 v35, v8, v9
	v_cvt_pk_bf16_f32 v36, v2, v3
	v_lshl_add_u64 v[40:41], s[12:13], 0, v[38:39]
	v_cvt_pk_bf16_f32 v37, v4, v5
	v_pk_mul_f32 v[42:43], v[66:67], v[2:3]
	v_lshl_add_u64 v[38:39], s[18:19], 0, v[38:39]
	v_pk_mul_f32 v[36:37], v[72:73], v[8:9]
	v_pk_mul_f32 v[34:35], v[70:71], v[6:7]
	v_pk_mul_f32 v[40:41], v[68:69], v[4:5]
	v_cvt_pk_bf16_f32 v34, v34, v35
	v_cvt_pk_bf16_f32 v35, v36, v37
	v_cvt_pk_bf16_f32 v36, v42, v43
	ds_swizzle_b32 v42, v96 offset:swizzle(SWAP,16)
	v_cvt_pk_bf16_f32 v37, v40, v41
	flat_store_dwordx4 v[38:39], v[34:37]
	v_cmp_eq_u32_e32 vcc, 0, v245
	s_waitcnt lgkmcnt(0)
	v_add_f32_e32 v36, v96, v42
	v_mov_b32_e32 v37, v36
	s_nop 1
	v_permlane32_swap_b32_e32 v36, v37
	v_lshl_add_u64 v[34:35], v[178:179], 3, s[20:21]
	s_and_saveexec_b64 s[30:31], vcc
	s_cbranch_execz .LBB0_1075
	v_add_f32_e32 v36, v36, v37
	v_mul_f32_e32 v36, 0x49800000, v36
	v_trunc_f32_e32 v36, v36
	v_mul_f32_e64 v37, |v36|, s78
	v_floor_f32_e32 v37, v37
	v_fma_f32 v38, v37, s74, |v36|
	v_cvt_u32_f32_e32 v38, v38
	v_cvt_u32_f32_e32 v37, v37
	v_ashrrev_i32_e32 v39, 31, v36
	v_xor_b32_e32 v36, v38, v39
	v_xor_b32_e32 v37, v37, v39
	v_sub_co_u32_e64 v36, s[8:9], v36, v39
	s_nop 1
	v_subb_co_u32_e64 v37, s[8:9], v37, v39, s[8:9]
	global_atomic_add_x2 v[34:35], v[36:37], off

.LBB0_1240:
	s_lshl_b32 s1, s1, 8
	s_add_i32 s1, s1, s72
	v_and_or_b32 v166, v156, 15, s1
	v_ashrrev_i32_e32 v177, 31, v176
	v_ashrrev_i32_e32 v167, 31, v166
	v_lshl_add_u64 v[170:171], v[176:177], 1, s[12:13]
	v_lshlrev_b64 v[188:189], 12, v[166:167]
	v_lshl_add_u64 v[186:187], v[170:171], 0, v[188:189]
	v_or_b32_e32 v198, 16, v166
	v_or_b32_e32 v200, 32, v166
	v_or_b32_e32 v174, 48, v166
	v_lshl_add_u64 v[246:247], v[186:187], 0, s[98:99]
	flat_load_dwordx4 v[182:185], v[246:247]
	v_ashrrev_i32_e32 v199, 31, v198
	v_ashrrev_i32_e32 v201, 31, v200
	v_ashrrev_i32_e32 v175, 31, v174
	v_lshlrev_b64 v[190:191], 12, v[198:199]
	v_lshlrev_b64 v[192:193], 12, v[200:201]
	v_lshlrev_b64 v[194:195], 12, v[174:175]
	v_lshl_add_u64 v[204:205], v[170:171], 0, v[190:191]
	v_lshl_add_u64 v[202:203], v[170:171], 0, v[192:193]
	v_lshl_add_u64 v[172:173], v[170:171], 0, v[194:195]
	v_lshl_add_u64 v[246:247], v[204:205], 0, s[98:99]
	flat_load_dwordx4 v[162:165], v[246:247]
	v_lshl_add_u64 v[246:247], v[202:203], 0, s[98:99]
	flat_load_dwordx4 v[158:161], v[246:247]
	v_lshl_add_u64 v[246:247], v[172:173], 0, s[98:99]
	flat_load_dwordx4 v[154:157], v[246:247]
	v_lshlrev_b64 v[196:197], 11, v[166:167]
	v_lshl_add_u64 v[206:207], v[196:197], 0, v[176:177]
	s_andn2_b64 vcc, exec, s[10:11]
	s_waitcnt vmcnt(0) lgkmcnt(0)
	v_rcp_f32_e32 v232, v232
	v_rcp_f32_e32 v233, v233
	v_rcp_f32_e32 v234, v234
	v_rcp_f32_e32 v235, v235
	v_rcp_f32_e32 v240, v240
	v_rcp_f32_e32 v241, v241
	v_rcp_f32_e32 v242, v242
	v_rcp_f32_e32 v243, v243
	s_nop 0
	v_lshlrev_b32_e32 v168, 16, v182
	v_and_b32_e32 v169, 0xffff0000, v182
	v_lshlrev_b32_e32 v208, 16, v184
	v_and_b32_e32 v209, 0xffff0000, v184
	v_lshlrev_b32_e32 v184, 16, v185
	v_and_b32_e32 v185, 0xffff0000, v185
	v_lshlrev_b32_e32 v182, 16, v183
	v_and_b32_e32 v183, 0xffff0000, v183
	v_pk_mul_f32 v[168:169], v[168:169], v[232:233]
	v_pk_fma_f32 v[168:169], v[150:151], v[110:111], v[168:169]
	v_pk_mul_f32 v[208:209], v[208:209], v[240:241]
	v_pk_fma_f32 v[150:151], v[146:147], v[106:107], v[208:209]
	v_pk_mul_f32 v[184:185], v[184:185], v[242:243]
	v_pk_fma_f32 v[146:147], v[148:149], v[108:109], v[184:185]
	v_cndmask_b32_e64 v148, 0, 1, s[10:11]
	v_pk_mul_f32 v[182:183], v[182:183], v[234:235]
	v_pk_fma_f32 v[152:153], v[152:153], v[112:113], v[182:183]
	v_cmp_ne_u32_e64 s[8:9], 1, v148
	v_cvt_pk_bf16_f32 v182, v168, v169
	v_cvt_pk_bf16_f32 v183, v152, v153
	v_cvt_pk_bf16_f32 v184, v150, v151
	v_cvt_pk_bf16_f32 v185, v146, v147
	s_cbranch_vccz .Lxs2_1
	flat_store_dwordx4 v[186:187], v[182:185]
.Lxs2_1:
	s_cbranch_vccnz .LBB0_1242
	v_pk_mul_f32 v[148:149], v[100:101], v[152:153]
	v_pk_mul_f32 v[182:183], v[98:99], v[168:169]
	v_pk_mul_f32 v[184:185], v[94:95], v[150:151]
	v_cvt_pk_bf16_f32 v182, v182, v183
	v_cvt_pk_bf16_f32 v183, v148, v149
	v_lshl_add_u64 v[148:149], v[206:207], 1, s[18:19]
	v_pk_mul_f32 v[186:187], v[96:97], v[146:147]
	v_cvt_pk_bf16_f32 v184, v184, v185
	s_nop 0
	v_cvt_pk_bf16_f32 v185, v186, v187
	flat_store_dwordx4 v[148:149], v[182:185]

.LBB0_1244:
	s_nop 1
	v_lshlrev_b32_e32 v182, 16, v162
	v_and_b32_e32 v183, 0xffff0000, v162
	v_lshlrev_b32_e32 v162, 16, v163
	v_and_b32_e32 v163, 0xffff0000, v163
	v_lshlrev_b32_e32 v184, 16, v164
	v_and_b32_e32 v185, 0xffff0000, v164
	v_lshlrev_b32_e32 v164, 16, v165
	v_and_b32_e32 v165, 0xffff0000, v165
	v_lshlrev_b64 v[198:199], 11, v[198:199]
	v_lshl_add_u64 v[148:149], v[198:199], 0, v[176:177]
	v_pk_mul_f32 v[162:163], v[162:163], v[234:235]
	v_pk_fma_f32 v[144:145], v[144:145], v[112:113], v[162:163]
	v_pk_mul_f32 v[182:183], v[182:183], v[232:233]
	v_pk_fma_f32 v[142:143], v[142:143], v[110:111], v[182:183]
	v_pk_mul_f32 v[184:185], v[184:185], v[240:241]
	v_pk_fma_f32 v[138:139], v[138:139], v[106:107], v[184:185]
	v_pk_mul_f32 v[164:165], v[164:165], v[242:243]
	v_pk_fma_f32 v[140:141], v[140:141], v[108:109], v[164:165]
	s_and_b64 vcc, exec, s[8:9]
	v_cvt_pk_bf16_f32 v162, v142, v143
	v_cvt_pk_bf16_f32 v163, v144, v145
	v_cvt_pk_bf16_f32 v164, v138, v139
	v_cvt_pk_bf16_f32 v165, v140, v141
	s_cbranch_vccz .Lxs2_2
	flat_store_dwordx4 v[204:205], v[162:165]
.Lxs2_2:
	s_cbranch_vccnz .LBB0_1246
	s_nop 0
	v_pk_mul_f32 v[164:165], v[100:101], v[144:145]
	v_pk_mul_f32 v[162:163], v[98:99], v[142:143]
	v_pk_mul_f32 v[182:183], v[96:97], v[140:141]
	v_pk_mul_f32 v[184:185], v[94:95], v[138:139]
	v_cvt_pk_bf16_f32 v162, v162, v163
	v_cvt_pk_bf16_f32 v163, v164, v165
	s_nop 0
	v_cvt_pk_bf16_f32 v164, v184, v185
	v_cvt_pk_bf16_f32 v165, v182, v183
	v_lshl_add_u64 v[182:183], v[148:149], 1, s[18:19]
	flat_store_dwordx4 v[182:183], v[162:165]

.LBB0_1248:
	v_lshlrev_b32_e32 v148, 16, v158
	v_and_b32_e32 v149, 0xffff0000, v158
	v_lshlrev_b32_e32 v158, 16, v159
	v_and_b32_e32 v159, 0xffff0000, v159
	v_lshlrev_b32_e32 v162, 16, v160
	v_and_b32_e32 v163, 0xffff0000, v160
	v_lshlrev_b32_e32 v164, 16, v161
	v_and_b32_e32 v165, 0xffff0000, v161
	v_lshlrev_b64 v[200:201], 11, v[200:201]
	v_lshl_add_u64 v[160:161], v[200:201], 0, v[176:177]
	v_pk_mul_f32 v[158:159], v[158:159], v[234:235]
	v_pk_fma_f32 v[136:137], v[136:137], v[112:113], v[158:159]
	v_pk_mul_f32 v[148:149], v[148:149], v[232:233]
	v_pk_fma_f32 v[134:135], v[134:135], v[110:111], v[148:149]
	v_pk_mul_f32 v[162:163], v[162:163], v[240:241]
	v_pk_fma_f32 v[148:149], v[130:131], v[106:107], v[162:163]
	v_pk_mul_f32 v[164:165], v[164:165], v[242:243]
	v_pk_fma_f32 v[158:159], v[132:133], v[108:109], v[164:165]
	s_and_b64 vcc, exec, s[8:9]
	v_cvt_pk_bf16_f32 v130, v134, v135
	v_cvt_pk_bf16_f32 v131, v136, v137
	v_cvt_pk_bf16_f32 v132, v148, v149
	v_cvt_pk_bf16_f32 v133, v158, v159
	s_cbranch_vccz .Lxs2_3
	flat_store_dwordx4 v[202:203], v[130:133]
.Lxs2_3:
	s_cbranch_vccnz .LBB0_1250
	s_nop 0
	v_pk_mul_f32 v[132:133], v[100:101], v[136:137]
	v_pk_mul_f32 v[130:131], v[98:99], v[134:135]
	v_pk_mul_f32 v[162:163], v[96:97], v[158:159]
	v_pk_mul_f32 v[164:165], v[94:95], v[148:149]
	v_cvt_pk_bf16_f32 v130, v130, v131
	v_cvt_pk_bf16_f32 v131, v132, v133
	s_nop 0
	v_cvt_pk_bf16_f32 v132, v164, v165
	v_cvt_pk_bf16_f32 v133, v162, v163
	v_lshl_add_u64 v[162:163], v[160:161], 1, s[18:19]
	flat_store_dwordx4 v[162:163], v[130:133]

.LBB0_1252:
	s_nop 1
	v_lshlrev_b32_e32 v132, 16, v154
	v_and_b32_e32 v133, 0xffff0000, v154
	v_lshlrev_b32_e32 v154, 16, v155
	v_and_b32_e32 v155, 0xffff0000, v155
	v_lshlrev_b32_e32 v160, 16, v156
	v_and_b32_e32 v161, 0xffff0000, v156
	v_lshlrev_b32_e32 v162, 16, v157
	v_and_b32_e32 v163, 0xffff0000, v157
	v_lshlrev_b64 v[202:203], 11, v[174:175]
	v_lshl_add_u64 v[130:131], v[202:203], 0, v[176:177]
	v_pk_mul_f32 v[154:155], v[154:155], v[234:235]
	v_pk_fma_f32 v[154:155], v[128:129], v[112:113], v[154:155]
	v_pk_mul_f32 v[132:133], v[132:133], v[232:233]
	v_pk_fma_f32 v[156:157], v[126:127], v[110:111], v[132:133]
	v_pk_mul_f32 v[160:161], v[160:161], v[240:241]
	v_pk_fma_f32 v[160:161], v[122:123], v[106:107], v[160:161]
	v_pk_mul_f32 v[162:163], v[162:163], v[242:243]
	v_pk_fma_f32 v[162:163], v[124:125], v[108:109], v[162:163]
	s_and_b64 vcc, exec, s[8:9]
	v_cvt_pk_bf16_f32 v122, v156, v157
	v_cvt_pk_bf16_f32 v123, v154, v155
	v_cvt_pk_bf16_f32 v124, v160, v161
	v_cvt_pk_bf16_f32 v125, v162, v163
	s_cbranch_vccz .Lxs2_4
	flat_store_dwordx4 v[172:173], v[122:125]
.Lxs2_4:
	s_cbranch_vccnz .LBB0_1254
	s_nop 0
	v_pk_mul_f32 v[124:125], v[100:101], v[154:155]
	v_pk_mul_f32 v[122:123], v[98:99], v[156:157]
	v_pk_mul_f32 v[126:127], v[96:97], v[162:163]
	v_pk_mul_f32 v[128:129], v[94:95], v[160:161]
	v_cvt_pk_bf16_f32 v122, v122, v123
	v_cvt_pk_bf16_f32 v123, v124, v125
	s_nop 0
	v_cvt_pk_bf16_f32 v124, v128, v129
	v_cvt_pk_bf16_f32 v125, v126, v127
	v_lshl_add_u64 v[126:127], v[130:131], 1, s[18:19]
	flat_store_dwordx4 v[126:127], v[122:125]

.LBB0_1256:
	v_add_u32_e32 v186, 0x80, v166
	v_ashrrev_i32_e32 v187, 31, v186
	v_lshlrev_b64 v[204:205], 12, v[186:187]
	v_add_u32_e32 v164, 0x90, v166
	v_add_u32_e32 v172, 0xa0, v166
	v_add_u32_e32 v220, 0xb0, v166
	v_lshl_add_u64 v[214:215], v[170:171], 0, v[204:205]
	v_ashrrev_i32_e32 v165, 31, v164
	v_ashrrev_i32_e32 v173, 31, v172
	v_ashrrev_i32_e32 v221, 31, v220
	v_lshl_add_u64 v[246:247], v[214:215], 0, s[98:99]
	flat_load_dwordx4 v[182:185], v[246:247]
	v_lshlrev_b64 v[206:207], 12, v[164:165]
	v_lshlrev_b64 v[208:209], 12, v[172:173]
	v_lshlrev_b64 v[210:211], 12, v[220:221]
	v_lshl_add_u64 v[174:175], v[170:171], 0, v[206:207]
	v_lshl_add_u64 v[222:223], v[170:171], 0, v[208:209]
	v_lshl_add_u64 v[218:219], v[170:171], 0, v[210:211]
	v_lshl_add_u64 v[246:247], v[174:175], 0, s[98:99]
	flat_load_dwordx4 v[130:133], v[246:247]
	v_lshl_add_u64 v[246:247], v[222:223], 0, s[98:99]
	flat_load_dwordx4 v[126:129], v[246:247]
	v_lshl_add_u64 v[246:247], v[218:219], 0, s[98:99]
	flat_load_dwordx4 v[122:125], v[246:247]
	v_lshlrev_b64 v[212:213], 11, v[186:187]
	v_lshl_add_u64 v[170:171], v[212:213], 0, v[176:177]
	s_and_b64 vcc, exec, s[8:9]
	s_waitcnt vmcnt(0) lgkmcnt(0)
	v_lshlrev_b32_e32 v216, 16, v182
	v_and_b32_e32 v217, 0xffff0000, v182
	v_lshlrev_b32_e32 v182, 16, v183
	v_and_b32_e32 v183, 0xffff0000, v183
	v_lshlrev_b32_e32 v230, 16, v184
	v_and_b32_e32 v231, 0xffff0000, v184
	v_lshlrev_b32_e32 v184, 16, v185
	v_and_b32_e32 v185, 0xffff0000, v185
	v_pk_mul_f32 v[182:183], v[182:183], v[234:235]
	v_pk_fma_f32 v[120:121], v[120:121], v[112:113], v[182:183]
	v_pk_mul_f32 v[216:217], v[216:217], v[232:233]
	v_pk_fma_f32 v[118:119], v[118:119], v[110:111], v[216:217]
	v_pk_mul_f32 v[230:231], v[230:231], v[240:241]
	v_pk_fma_f32 v[114:115], v[114:115], v[106:107], v[230:231]
	v_pk_mul_f32 v[184:185], v[184:185], v[242:243]
	v_pk_fma_f32 v[116:117], v[116:117], v[108:109], v[184:185]
	v_cvt_pk_bf16_f32 v182, v118, v119
	v_cvt_pk_bf16_f32 v183, v120, v121
	v_cvt_pk_bf16_f32 v184, v114, v115
	s_nop 0
	v_cvt_pk_bf16_f32 v185, v116, v117
	s_cbranch_vccz .Lxs2_5
	flat_store_dwordx4 v[214:215], v[182:185]
.Lxs2_5:
	s_cbranch_vccnz .LBB0_1258
	s_nop 0
	v_pk_mul_f32 v[184:185], v[100:101], v[120:121]
	v_pk_mul_f32 v[182:183], v[98:99], v[118:119]
	v_pk_mul_f32 v[186:187], v[96:97], v[116:117]
	v_pk_mul_f32 v[214:215], v[94:95], v[114:115]
	v_cvt_pk_bf16_f32 v182, v182, v183
	v_cvt_pk_bf16_f32 v183, v184, v185
	s_nop 0
	v_cvt_pk_bf16_f32 v184, v214, v215
	v_cvt_pk_bf16_f32 v185, v186, v187
	v_lshl_add_u64 v[186:187], v[170:171], 1, s[18:19]
	flat_store_dwordx4 v[186:187], v[182:185]

.LBB0_1260:
	v_lshlrev_b32_e32 v170, 16, v130
	v_and_b32_e32 v171, 0xffff0000, v130
	v_lshlrev_b32_e32 v130, 16, v131
	v_and_b32_e32 v131, 0xffff0000, v131
	v_lshlrev_b32_e32 v182, 16, v132
	v_and_b32_e32 v183, 0xffff0000, v132
	v_lshlrev_b32_e32 v184, 16, v133
	v_and_b32_e32 v185, 0xffff0000, v133
	v_lshlrev_b64 v[214:215], 11, v[164:165]
	v_lshl_add_u64 v[216:217], v[214:215], 0, v[176:177]
	v_pk_mul_f32 v[130:131], v[130:131], v[234:235]
	v_pk_fma_f32 v[130:131], v[88:89], v[112:113], v[130:131]
	v_pk_mul_f32 v[170:171], v[170:171], v[232:233]
	v_pk_fma_f32 v[132:133], v[86:87], v[110:111], v[170:171]
	v_pk_mul_f32 v[182:183], v[182:183], v[240:241]
	v_pk_fma_f32 v[164:165], v[82:83], v[106:107], v[182:183]
	v_pk_mul_f32 v[184:185], v[184:185], v[242:243]
	v_pk_fma_f32 v[170:171], v[84:85], v[108:109], v[184:185]
	s_and_b64 vcc, exec, s[8:9]
	v_cvt_pk_bf16_f32 v82, v132, v133
	v_cvt_pk_bf16_f32 v83, v130, v131
	v_cvt_pk_bf16_f32 v84, v164, v165
	v_cvt_pk_bf16_f32 v85, v170, v171
	s_cbranch_vccz .Lxs2_6
	flat_store_dwordx4 v[174:175], v[82:85]
.Lxs2_6:
	s_cbranch_vccnz .LBB0_1262
	s_nop 0
	v_pk_mul_f32 v[84:85], v[100:101], v[130:131]
	v_pk_mul_f32 v[82:83], v[98:99], v[132:133]
	v_pk_mul_f32 v[86:87], v[96:97], v[170:171]
	v_pk_mul_f32 v[88:89], v[94:95], v[164:165]
	v_cvt_pk_bf16_f32 v82, v82, v83
	v_cvt_pk_bf16_f32 v83, v84, v85
	s_nop 0
	v_cvt_pk_bf16_f32 v84, v88, v89
	v_cvt_pk_bf16_f32 v85, v86, v87
	v_lshl_add_u64 v[86:87], v[216:217], 1, s[18:19]
	flat_store_dwordx4 v[86:87], v[82:85]

.LBB0_1264:
	s_nop 1
	v_lshlrev_b32_e32 v84, 16, v126
	v_and_b32_e32 v85, 0xffff0000, v126
	v_lshlrev_b32_e32 v86, 16, v127
	v_and_b32_e32 v87, 0xffff0000, v127
	v_lshlrev_b32_e32 v88, 16, v128
	v_and_b32_e32 v89, 0xffff0000, v128
	v_lshlrev_b32_e32 v174, 16, v129
	v_and_b32_e32 v175, 0xffff0000, v129
	v_lshlrev_b64 v[216:217], 11, v[172:173]
	v_lshl_add_u64 v[82:83], v[216:217], 0, v[176:177]
	v_pk_mul_f32 v[86:87], v[86:87], v[234:235]
	v_pk_fma_f32 v[126:127], v[80:81], v[112:113], v[86:87]
	v_pk_mul_f32 v[84:85], v[84:85], v[232:233]
	v_pk_fma_f32 v[128:129], v[78:79], v[110:111], v[84:85]
	v_pk_mul_f32 v[88:89], v[88:89], v[240:241]
	v_pk_fma_f32 v[172:173], v[74:75], v[106:107], v[88:89]
	v_pk_mul_f32 v[174:175], v[174:175], v[242:243]
	v_pk_fma_f32 v[174:175], v[76:77], v[108:109], v[174:175]
	s_and_b64 vcc, exec, s[8:9]
	v_cvt_pk_bf16_f32 v74, v128, v129
	v_cvt_pk_bf16_f32 v75, v126, v127
	v_cvt_pk_bf16_f32 v76, v172, v173
	v_cvt_pk_bf16_f32 v77, v174, v175
	s_cbranch_vccz .Lxs2_7
	flat_store_dwordx4 v[222:223], v[74:77]
.Lxs2_7:
	s_cbranch_vccnz .LBB0_1266
	s_nop 0
	v_pk_mul_f32 v[76:77], v[100:101], v[126:127]
	v_pk_mul_f32 v[74:75], v[98:99], v[128:129]
	v_pk_mul_f32 v[78:79], v[96:97], v[174:175]
	v_pk_mul_f32 v[80:81], v[94:95], v[172:173]
	v_cvt_pk_bf16_f32 v74, v74, v75
	v_cvt_pk_bf16_f32 v75, v76, v77
	s_nop 0
	v_cvt_pk_bf16_f32 v76, v80, v81
	v_cvt_pk_bf16_f32 v77, v78, v79
	v_lshl_add_u64 v[78:79], v[82:83], 1, s[18:19]
	flat_store_dwordx4 v[78:79], v[74:77]

.LBB0_1268:
	s_nop 1
	v_lshlrev_b32_e32 v76, 16, v122
	v_and_b32_e32 v77, 0xffff0000, v122
	v_lshlrev_b32_e32 v78, 16, v123
	v_and_b32_e32 v79, 0xffff0000, v123
	v_lshlrev_b32_e32 v80, 16, v124
	v_and_b32_e32 v81, 0xffff0000, v124
	v_lshlrev_b32_e32 v82, 16, v125
	v_and_b32_e32 v83, 0xffff0000, v125
	v_lshlrev_b64 v[122:123], 11, v[220:221]
	v_lshl_add_u64 v[74:75], v[122:123], 0, v[176:177]
	v_pk_mul_f32 v[78:79], v[78:79], v[234:235]
	v_pk_fma_f32 v[112:113], v[72:73], v[112:113], v[78:79]
	v_pk_mul_f32 v[76:77], v[76:77], v[232:233]
	v_pk_fma_f32 v[110:111], v[70:71], v[110:111], v[76:77]
	v_pk_mul_f32 v[80:81], v[80:81], v[240:241]
	v_pk_fma_f32 v[106:107], v[66:67], v[106:107], v[80:81]
	v_pk_mul_f32 v[82:83], v[82:83], v[242:243]
	v_pk_fma_f32 v[108:109], v[68:69], v[108:109], v[82:83]
	s_and_b64 vcc, exec, s[8:9]
	v_cvt_pk_bf16_f32 v66, v110, v111
	v_cvt_pk_bf16_f32 v67, v112, v113
	v_cvt_pk_bf16_f32 v68, v106, v107
	v_cvt_pk_bf16_f32 v69, v108, v109
	s_cbranch_vccz .Lxs2_8
	flat_store_dwordx4 v[218:219], v[66:69]
.Lxs2_8:
	s_cbranch_vccnz .LBB0_1270
	s_nop 0
	v_pk_mul_f32 v[68:69], v[100:101], v[112:113]
	v_pk_mul_f32 v[66:67], v[98:99], v[110:111]
	v_pk_mul_f32 v[70:71], v[96:97], v[108:109]
	v_pk_mul_f32 v[72:73], v[94:95], v[106:107]
	v_cvt_pk_bf16_f32 v66, v66, v67
	v_cvt_pk_bf16_f32 v67, v68, v69
	s_nop 0
	v_cvt_pk_bf16_f32 v68, v72, v73
	v_cvt_pk_bf16_f32 v69, v70, v71
	v_lshl_add_u64 v[70:71], v[74:75], 1, s[18:19]
	flat_store_dwordx4 v[70:71], v[66:69]

.LBB0_1276:
	v_ashrrev_i32_e32 v103, 31, v102
	v_lshl_add_u64 v[90:91], s[12:13], 0, v[188:189]
	v_lshlrev_b64 v[104:105], 1, v[102:103]
	v_lshl_add_u64 v[186:187], v[90:91], 0, v[104:105]
	v_lshl_add_u64 v[90:91], s[12:13], 0, v[190:191]
	v_lshl_add_u64 v[246:247], v[186:187], 0, s[98:99]
	flat_load_dwordx4 v[182:185], v[246:247]
	v_lshl_add_u64 v[92:93], s[12:13], 0, v[192:193]
	v_lshl_add_u64 v[94:95], s[12:13], 0, v[194:195]
	v_lshl_add_u64 v[178:179], v[90:91], 0, v[104:105]
	v_lshl_add_u64 v[176:177], v[92:93], 0, v[104:105]
	v_lshl_add_u64 v[124:125], v[94:95], 0, v[104:105]
	v_lshl_add_u64 v[246:247], v[178:179], 0, s[98:99]
	flat_load_dwordx4 v[98:101], v[246:247]
	v_lshl_add_u64 v[246:247], v[176:177], 0, s[98:99]
	flat_load_dwordx4 v[94:97], v[246:247]
	v_lshl_add_u64 v[246:247], v[124:125], 0, s[98:99]
	flat_load_dwordx4 v[90:93], v[246:247]
	v_lshl_add_u64 v[188:189], v[196:197], 0, v[102:103]
	s_and_b64 vcc, exec, s[8:9]
	s_waitcnt vmcnt(0) lgkmcnt(0)
	v_rcp_f32_e32 v232, v232
	v_rcp_f32_e32 v233, v233
	v_rcp_f32_e32 v234, v234
	v_rcp_f32_e32 v235, v235
	v_rcp_f32_e32 v240, v240
	v_rcp_f32_e32 v241, v241
	v_rcp_f32_e32 v242, v242
	v_rcp_f32_e32 v243, v243
	s_nop 0
	v_lshlrev_b32_e32 v190, 16, v182
	v_and_b32_e32 v191, 0xffff0000, v182
	v_lshlrev_b32_e32 v182, 16, v183
	v_and_b32_e32 v183, 0xffff0000, v183
	v_lshlrev_b32_e32 v192, 16, v184
	v_and_b32_e32 v193, 0xffff0000, v184
	v_lshlrev_b32_e32 v184, 16, v185
	v_and_b32_e32 v185, 0xffff0000, v185
	v_pk_mul_f32 v[182:183], v[182:183], v[234:235]
	v_pk_fma_f32 v[64:65], v[64:65], v[88:89], v[182:183]
	v_pk_mul_f32 v[190:191], v[190:191], v[232:233]
	v_pk_fma_f32 v[62:63], v[62:63], v[86:87], v[190:191]
	v_pk_mul_f32 v[192:193], v[192:193], v[240:241]
	v_pk_fma_f32 v[58:59], v[58:59], v[82:83], v[192:193]
	v_pk_mul_f32 v[184:185], v[184:185], v[242:243]
	v_pk_fma_f32 v[60:61], v[60:61], v[84:85], v[184:185]
	v_cvt_pk_bf16_f32 v182, v62, v63
	v_cvt_pk_bf16_f32 v183, v64, v65
	v_cvt_pk_bf16_f32 v184, v58, v59
	s_nop 0
	v_cvt_pk_bf16_f32 v185, v60, v61
	s_cbranch_vccz .Lxs2_9
	flat_store_dwordx4 v[186:187], v[182:185]
.Lxs2_9:
	s_cbranch_vccnz .LBB0_1278
	s_nop 0
	v_pk_mul_f32 v[184:185], v[76:77], v[64:65]
	v_pk_mul_f32 v[182:183], v[74:75], v[62:63]
	v_pk_mul_f32 v[186:187], v[72:73], v[60:61]
	v_pk_mul_f32 v[190:191], v[70:71], v[58:59]
	v_cvt_pk_bf16_f32 v182, v182, v183
	v_cvt_pk_bf16_f32 v183, v184, v185
	s_nop 0
	v_cvt_pk_bf16_f32 v184, v190, v191
	v_cvt_pk_bf16_f32 v185, v186, v187
	v_lshl_add_u64 v[186:187], v[188:189], 1, s[18:19]
	flat_store_dwordx4 v[186:187], v[182:185]

.LBB0_1280:
	s_nop 1
	v_lshlrev_b32_e32 v182, 16, v98
	v_and_b32_e32 v183, 0xffff0000, v98
	v_lshlrev_b32_e32 v184, 16, v99
	v_and_b32_e32 v185, 0xffff0000, v99
	v_lshlrev_b32_e32 v186, 16, v100
	v_and_b32_e32 v187, 0xffff0000, v100
	v_lshlrev_b32_e32 v100, 16, v101
	v_and_b32_e32 v101, 0xffff0000, v101
	v_lshl_add_u64 v[98:99], v[198:199], 0, v[102:103]
	v_pk_mul_f32 v[184:185], v[184:185], v[234:235]
	v_pk_fma_f32 v[56:57], v[56:57], v[88:89], v[184:185]
	v_pk_mul_f32 v[182:183], v[182:183], v[232:233]
	v_pk_fma_f32 v[54:55], v[54:55], v[86:87], v[182:183]
	v_pk_mul_f32 v[186:187], v[186:187], v[240:241]
	v_pk_fma_f32 v[50:51], v[50:51], v[82:83], v[186:187]
	v_pk_mul_f32 v[100:101], v[100:101], v[242:243]
	v_pk_fma_f32 v[52:53], v[52:53], v[84:85], v[100:101]
	s_and_b64 vcc, exec, s[8:9]
	v_cvt_pk_bf16_f32 v182, v54, v55
	v_cvt_pk_bf16_f32 v183, v56, v57
	v_cvt_pk_bf16_f32 v184, v50, v51
	v_cvt_pk_bf16_f32 v185, v52, v53
	s_cbranch_vccz .Lxs2_10
	flat_store_dwordx4 v[178:179], v[182:185]
.Lxs2_10:
	s_cbranch_vccnz .LBB0_1282
	v_pk_mul_f32 v[100:101], v[76:77], v[56:57]
	v_pk_mul_f32 v[178:179], v[74:75], v[54:55]
	v_pk_mul_f32 v[184:185], v[70:71], v[50:51]
	v_cvt_pk_bf16_f32 v182, v178, v179
	v_cvt_pk_bf16_f32 v183, v100, v101
	v_lshl_add_u64 v[100:101], v[98:99], 1, s[18:19]
	v_pk_mul_f32 v[186:187], v[72:73], v[52:53]
	v_cvt_pk_bf16_f32 v184, v184, v185
	s_nop 0
	v_cvt_pk_bf16_f32 v185, v186, v187
	flat_store_dwordx4 v[100:101], v[182:185]

.LBB0_1284:
	v_lshlrev_b32_e32 v100, 16, v94
	v_and_b32_e32 v101, 0xffff0000, v94
	v_lshlrev_b32_e32 v94, 16, v95
	v_and_b32_e32 v95, 0xffff0000, v95
	v_lshlrev_b32_e32 v178, 16, v96
	v_and_b32_e32 v179, 0xffff0000, v96
	v_lshlrev_b32_e32 v96, 16, v97
	v_and_b32_e32 v97, 0xffff0000, v97
	v_lshl_add_u64 v[98:99], v[200:201], 0, v[102:103]
	v_pk_mul_f32 v[94:95], v[94:95], v[234:235]
	v_pk_fma_f32 v[48:49], v[48:49], v[88:89], v[94:95]
	v_pk_mul_f32 v[100:101], v[100:101], v[232:233]
	v_pk_fma_f32 v[46:47], v[46:47], v[86:87], v[100:101]
	v_pk_mul_f32 v[178:179], v[178:179], v[240:241]
	v_pk_fma_f32 v[94:95], v[42:43], v[82:83], v[178:179]
	v_pk_mul_f32 v[96:97], v[96:97], v[242:243]
	v_pk_fma_f32 v[96:97], v[44:45], v[84:85], v[96:97]
	s_and_b64 vcc, exec, s[8:9]
	v_cvt_pk_bf16_f32 v42, v46, v47
	v_cvt_pk_bf16_f32 v43, v48, v49
	v_cvt_pk_bf16_f32 v44, v94, v95
	v_cvt_pk_bf16_f32 v45, v96, v97
	s_cbranch_vccz .Lxs2_11
	flat_store_dwordx4 v[176:177], v[42:45]
.Lxs2_11:
	s_cbranch_vccnz .LBB0_1286
	s_nop 0
	v_pk_mul_f32 v[44:45], v[76:77], v[48:49]
	v_pk_mul_f32 v[42:43], v[74:75], v[46:47]
	v_pk_mul_f32 v[100:101], v[72:73], v[96:97]
	v_pk_mul_f32 v[176:177], v[70:71], v[94:95]
	v_cvt_pk_bf16_f32 v42, v42, v43
	v_cvt_pk_bf16_f32 v43, v44, v45
	s_nop 0
	v_cvt_pk_bf16_f32 v44, v176, v177
	v_cvt_pk_bf16_f32 v45, v100, v101
	v_lshl_add_u64 v[100:101], v[98:99], 1, s[18:19]
	flat_store_dwordx4 v[100:101], v[42:45]

.LBB0_1288:
	s_nop 1
	v_lshlrev_b32_e32 v44, 16, v90
	v_and_b32_e32 v45, 0xffff0000, v90
	v_lshlrev_b32_e32 v90, 16, v91
	v_and_b32_e32 v91, 0xffff0000, v91
	v_lshlrev_b32_e32 v98, 16, v92
	v_and_b32_e32 v99, 0xffff0000, v92
	v_lshlrev_b32_e32 v100, 16, v93
	v_and_b32_e32 v101, 0xffff0000, v93
	v_lshl_add_u64 v[42:43], v[202:203], 0, v[102:103]
	v_pk_mul_f32 v[90:91], v[90:91], v[234:235]
	v_pk_fma_f32 v[90:91], v[40:41], v[88:89], v[90:91]
	v_pk_mul_f32 v[44:45], v[44:45], v[232:233]
	v_pk_fma_f32 v[92:93], v[38:39], v[86:87], v[44:45]
	v_pk_mul_f32 v[98:99], v[98:99], v[240:241]
	v_pk_fma_f32 v[98:99], v[34:35], v[82:83], v[98:99]
	v_pk_mul_f32 v[100:101], v[100:101], v[242:243]
	v_pk_fma_f32 v[100:101], v[36:37], v[84:85], v[100:101]
	s_and_b64 vcc, exec, s[8:9]
	v_cvt_pk_bf16_f32 v34, v92, v93
	v_cvt_pk_bf16_f32 v35, v90, v91
	v_cvt_pk_bf16_f32 v36, v98, v99
	v_cvt_pk_bf16_f32 v37, v100, v101
	s_cbranch_vccz .Lxs2_12
	flat_store_dwordx4 v[124:125], v[34:37]
.Lxs2_12:
	s_cbranch_vccnz .LBB0_1290
	s_nop 0
	v_pk_mul_f32 v[36:37], v[76:77], v[90:91]
	v_pk_mul_f32 v[34:35], v[74:75], v[92:93]
	v_pk_mul_f32 v[38:39], v[72:73], v[100:101]
	v_pk_mul_f32 v[40:41], v[70:71], v[98:99]
	v_cvt_pk_bf16_f32 v34, v34, v35
	v_cvt_pk_bf16_f32 v35, v36, v37
	s_nop 0
	v_cvt_pk_bf16_f32 v36, v40, v41
	v_cvt_pk_bf16_f32 v37, v38, v39
	v_lshl_add_u64 v[38:39], v[42:43], 1, s[18:19]
	flat_store_dwordx4 v[38:39], v[34:37]

.LBB0_1292:
	s_nop 1
	v_lshl_add_u64 v[34:35], s[12:13], 0, v[204:205]
	v_lshl_add_u64 v[186:187], v[34:35], 0, v[104:105]
	v_lshl_add_u64 v[34:35], s[12:13], 0, v[206:207]
	v_lshl_add_u64 v[246:247], v[186:187], 0, s[98:99]
	flat_load_dwordx4 v[182:185], v[246:247]
	v_lshl_add_u64 v[36:37], s[12:13], 0, v[208:209]
	v_lshl_add_u64 v[38:39], s[12:13], 0, v[210:211]
	v_lshl_add_u64 v[176:177], v[34:35], 0, v[104:105]
	v_lshl_add_u64 v[124:125], v[36:37], 0, v[104:105]
	v_lshl_add_u64 v[104:105], v[38:39], 0, v[104:105]
	v_lshl_add_u64 v[246:247], v[176:177], 0, s[98:99]
	flat_load_dwordx4 v[42:45], v[246:247]
	v_lshl_add_u64 v[246:247], v[124:125], 0, s[98:99]
	flat_load_dwordx4 v[38:41], v[246:247]
	v_lshl_add_u64 v[246:247], v[104:105], 0, s[98:99]
	flat_load_dwordx4 v[34:37], v[246:247]
	v_lshl_add_u64 v[178:179], v[212:213], 0, v[102:103]
	s_and_b64 vcc, exec, s[8:9]
	s_waitcnt vmcnt(0) lgkmcnt(0)
	v_lshlrev_b32_e32 v188, 16, v182
	v_and_b32_e32 v189, 0xffff0000, v182
	v_lshlrev_b32_e32 v182, 16, v183
	v_and_b32_e32 v183, 0xffff0000, v183
	v_lshlrev_b32_e32 v190, 16, v184
	v_and_b32_e32 v191, 0xffff0000, v184
	v_lshlrev_b32_e32 v184, 16, v185
	v_and_b32_e32 v185, 0xffff0000, v185
	v_pk_mul_f32 v[182:183], v[182:183], v[234:235]
	v_pk_fma_f32 v[32:33], v[32:33], v[88:89], v[182:183]
	v_pk_mul_f32 v[188:189], v[188:189], v[232:233]
	v_pk_fma_f32 v[30:31], v[30:31], v[86:87], v[188:189]
	v_pk_mul_f32 v[190:191], v[190:191], v[240:241]
	v_pk_fma_f32 v[26:27], v[26:27], v[82:83], v[190:191]
	v_pk_mul_f32 v[184:185], v[184:185], v[242:243]
	v_pk_fma_f32 v[28:29], v[28:29], v[84:85], v[184:185]
	v_cvt_pk_bf16_f32 v182, v30, v31
	v_cvt_pk_bf16_f32 v183, v32, v33
	v_cvt_pk_bf16_f32 v184, v26, v27
	s_nop 0
	v_cvt_pk_bf16_f32 v185, v28, v29
	s_cbranch_vccz .Lxs2_13
	flat_store_dwordx4 v[186:187], v[182:185]
.Lxs2_13:
	s_cbranch_vccnz .LBB0_1294
	s_nop 0
	v_pk_mul_f32 v[184:185], v[76:77], v[32:33]
	v_pk_mul_f32 v[182:183], v[74:75], v[30:31]
	v_pk_mul_f32 v[186:187], v[72:73], v[28:29]
	v_pk_mul_f32 v[188:189], v[70:71], v[26:27]
	v_cvt_pk_bf16_f32 v182, v182, v183
	v_cvt_pk_bf16_f32 v183, v184, v185
	s_nop 0
	v_cvt_pk_bf16_f32 v184, v188, v189
	v_cvt_pk_bf16_f32 v185, v186, v187
	v_lshl_add_u64 v[186:187], v[178:179], 1, s[18:19]
	flat_store_dwordx4 v[186:187], v[182:185]

.LBB0_1296:
	v_lshlrev_b32_e32 v178, 16, v42
	v_and_b32_e32 v179, 0xffff0000, v42
	v_lshlrev_b32_e32 v182, 16, v43
	v_and_b32_e32 v183, 0xffff0000, v43
	v_lshlrev_b32_e32 v184, 16, v44
	v_and_b32_e32 v185, 0xffff0000, v44
	v_lshlrev_b32_e32 v44, 16, v45
	v_and_b32_e32 v45, 0xffff0000, v45
	v_lshl_add_u64 v[42:43], v[214:215], 0, v[102:103]
	v_pk_mul_f32 v[182:183], v[182:183], v[234:235]
	v_pk_fma_f32 v[24:25], v[24:25], v[88:89], v[182:183]
	v_pk_mul_f32 v[178:179], v[178:179], v[232:233]
	v_pk_fma_f32 v[22:23], v[22:23], v[86:87], v[178:179]
	v_pk_mul_f32 v[184:185], v[184:185], v[240:241]
	v_pk_fma_f32 v[18:19], v[18:19], v[82:83], v[184:185]
	v_pk_mul_f32 v[44:45], v[44:45], v[242:243]
	v_pk_fma_f32 v[20:21], v[20:21], v[84:85], v[44:45]
	s_and_b64 vcc, exec, s[8:9]
	v_cvt_pk_bf16_f32 v182, v22, v23
	v_cvt_pk_bf16_f32 v183, v24, v25
	v_cvt_pk_bf16_f32 v184, v18, v19
	v_cvt_pk_bf16_f32 v185, v20, v21
	s_cbranch_vccz .Lxs2_14
	flat_store_dwordx4 v[176:177], v[182:185]
.Lxs2_14:
	s_cbranch_vccnz .LBB0_1298
	v_pk_mul_f32 v[44:45], v[76:77], v[24:25]
	v_pk_mul_f32 v[176:177], v[74:75], v[22:23]
	v_pk_mul_f32 v[178:179], v[70:71], v[18:19]
	v_cvt_pk_bf16_f32 v176, v176, v177
	v_cvt_pk_bf16_f32 v177, v44, v45
	v_lshl_add_u64 v[44:45], v[42:43], 1, s[18:19]
	v_pk_mul_f32 v[182:183], v[72:73], v[20:21]
	v_cvt_pk_bf16_f32 v178, v178, v179
	s_nop 0
	v_cvt_pk_bf16_f32 v179, v182, v183
	flat_store_dwordx4 v[44:45], v[176:179]

.LBB0_1300:
	v_lshlrev_b32_e32 v42, 16, v38
	v_and_b32_e32 v43, 0xffff0000, v38
	v_lshlrev_b32_e32 v44, 16, v39
	v_and_b32_e32 v45, 0xffff0000, v39
	v_lshlrev_b32_e32 v176, 16, v40
	v_and_b32_e32 v177, 0xffff0000, v40
	v_lshlrev_b32_e32 v40, 16, v41
	v_and_b32_e32 v41, 0xffff0000, v41
	v_lshl_add_u64 v[38:39], v[216:217], 0, v[102:103]
	v_pk_mul_f32 v[44:45], v[44:45], v[234:235]
	v_pk_fma_f32 v[16:17], v[16:17], v[88:89], v[44:45]
	v_pk_mul_f32 v[42:43], v[42:43], v[232:233]
	v_pk_fma_f32 v[14:15], v[14:15], v[86:87], v[42:43]
	v_pk_mul_f32 v[176:177], v[176:177], v[240:241]
	v_pk_fma_f32 v[10:11], v[10:11], v[82:83], v[176:177]
	v_pk_mul_f32 v[40:41], v[40:41], v[242:243]
	v_pk_fma_f32 v[12:13], v[12:13], v[84:85], v[40:41]
	s_and_b64 vcc, exec, s[8:9]
	v_cvt_pk_bf16_f32 v40, v14, v15
	v_cvt_pk_bf16_f32 v41, v16, v17
	v_cvt_pk_bf16_f32 v42, v10, v11
	v_cvt_pk_bf16_f32 v43, v12, v13
	s_cbranch_vccz .Lxs2_15
	flat_store_dwordx4 v[124:125], v[40:43]
.Lxs2_15:
	s_cbranch_vccnz .LBB0_1302
	s_nop 0
	v_pk_mul_f32 v[42:43], v[76:77], v[16:17]
	v_pk_mul_f32 v[40:41], v[74:75], v[14:15]
	v_pk_mul_f32 v[44:45], v[72:73], v[12:13]
	v_pk_mul_f32 v[124:125], v[70:71], v[10:11]
	v_cvt_pk_bf16_f32 v40, v40, v41
	v_cvt_pk_bf16_f32 v41, v42, v43
	s_nop 0
	v_cvt_pk_bf16_f32 v42, v124, v125
	v_cvt_pk_bf16_f32 v43, v44, v45
	v_lshl_add_u64 v[44:45], v[38:39], 1, s[18:19]
	flat_store_dwordx4 v[44:45], v[40:43]

.LBB0_1304:
	v_lshlrev_b32_e32 v38, 16, v34
	v_and_b32_e32 v39, 0xffff0000, v34
	v_lshlrev_b32_e32 v40, 16, v35
	v_and_b32_e32 v41, 0xffff0000, v35
	v_lshlrev_b32_e32 v42, 16, v36
	v_and_b32_e32 v43, 0xffff0000, v36
	v_lshlrev_b32_e32 v36, 16, v37
	v_and_b32_e32 v37, 0xffff0000, v37
	v_lshl_add_u64 v[34:35], v[122:123], 0, v[102:103]
	v_pk_mul_f32 v[40:41], v[40:41], v[234:235]
	v_pk_fma_f32 v[8:9], v[8:9], v[88:89], v[40:41]
	v_pk_mul_f32 v[38:39], v[38:39], v[232:233]
	v_pk_fma_f32 v[6:7], v[6:7], v[86:87], v[38:39]
	v_pk_mul_f32 v[42:43], v[42:43], v[240:241]
	v_pk_fma_f32 v[2:3], v[2:3], v[82:83], v[42:43]
	v_pk_mul_f32 v[36:37], v[36:37], v[242:243]
	v_pk_fma_f32 v[4:5], v[4:5], v[84:85], v[36:37]
	s_and_b64 vcc, exec, s[8:9]
	v_cvt_pk_bf16_f32 v36, v6, v7
	v_cvt_pk_bf16_f32 v37, v8, v9
	v_cvt_pk_bf16_f32 v38, v2, v3
	v_cvt_pk_bf16_f32 v39, v4, v5
	s_cbranch_vccz .Lxs2_16
	flat_store_dwordx4 v[104:105], v[36:39]
.Lxs2_16:
	s_cbranch_vccnz .LBB0_1324
	s_nop 0
	v_pk_mul_f32 v[38:39], v[76:77], v[8:9]
	v_pk_mul_f32 v[36:37], v[74:75], v[6:7]
	v_pk_mul_f32 v[40:41], v[72:73], v[4:5]
	v_pk_mul_f32 v[42:43], v[70:71], v[2:3]
	v_cvt_pk_bf16_f32 v36, v36, v37
	v_cvt_pk_bf16_f32 v37, v38, v39
	s_nop 0
	v_cvt_pk_bf16_f32 v38, v42, v43
	v_cvt_pk_bf16_f32 v39, v40, v41
	v_lshl_add_u64 v[40:41], v[34:35], 1, s[18:19]
	flat_store_dwordx4 v[40:41], v[36:39]
	s_and_b64 vcc, exec, s[6:7]
	s_cbranch_vccz .LBB0_1325
